# silu gate divisions as v_rcp+v_mul in GLA output stage and attention merge epilogue; attention epilogue 8-byte row stores paired into 16-byte stores via v_permlane32_swap
# speedup vs baseline: 1.0485x; 1.0066x over previous
; DI unsigned pk2(float lo, float hi) { f32x2 v = {lo, hi}; return __builtin_bit_cast(unsigned, __builtin_convertvector(v, bf2_t)); }
; DI float bflo(unsigned w) { return __uint_as_float(w << 16); }
; DI float bfhi(unsigned w) { return __uint_as_float(w & 0xffff0000u); }
; DI void attn_unit(const Params& p, int b, int h, int qb, LAS unsigned char* lds, int tid, int lane, int wave) {
;     ...
;     if (g == 0) {
;         const float m1 = MB[64 * 64], l1 = MB[65 * 64];
;         const float m = fmaxf(mrow, m1);
;         const float a0 = __builtin_amdgcn_exp2f(mrow - m), a1 = __builtin_amdgcn_exp2f(m1 - m);
;         const float inv = 1.0f / (lrow * a0 + l1 * a1);
;         const size_t tok = tokb + qr0 + r;
;         const bf16_t* gp = Z + tok * ZLD + Z_MG + h * 128 + 4 * hh;
;         bf16_t* op = OB + tok * DM + 512 + h * 128 + 4 * hh;
;         u32x2 gw[4][4];
; #pragma unroll
;         for (int i = 0; i < 4; ++i)
; #pragma unroll
;             for (int q = 0; q < 4; ++q) gw[i][q] = *(const u32x2*)(gp + i * 32 + q * 8);
; #pragma unroll
;         for (int i = 0; i < 4; ++i)
; #pragma unroll
;             for (int q = 0; q < 4; ++q) {
;                 float gv[4] = {bflo(gw[i][q].x), bfhi(gw[i][q].x), bflo(gw[i][q].y), bfhi(gw[i][q].y)}; float ov[4];
; #pragma unroll
;                 for (int e = 0; e < 4; ++e) { const float val = (o[i][q * 4 + e] * a0 + MB[(i * 16 + q * 4 + e) * 64] * a1) * inv; ov[e] = val * (gv[e] / (1.f + __expf(-gv[e]))); }
;                 *(u32x2*)(op + i * 32 + q * 8) = (u32x2){pk2(ov[0], ov[1]), pk2(ov[2], ov[3])};
.LBB0_442:
	s_cmp_gt_u32 s3, 3
	s_waitcnt lgkmcnt(0)
	s_barrier
	s_cbranch_scc1 .LBB0_444
	ds_read2st64_b32 v[70:71], v104 offset0:64 offset1:65
	v_max_f32_e32 v0, v204, v204
	s_lshl_b32 s0, s2, 8
	s_mov_b32 s1, s93
	v_ashrrev_i32_e32 v183, 31, v182
	s_waitcnt lgkmcnt(0)
	v_max_f32_e32 v66, v70, v70
	v_max_f32_e32 v0, v0, v66
	v_sub_f32_e32 v66, v204, v0
	v_sub_f32_e32 v0, v70, v0
	v_exp_f32_e32 v66, v66
	v_exp_f32_e32 v67, v0
	v_mov_b32_e32 v69, v71
	v_lshlrev_b32_e32 v0, 12, v202
	v_lshlrev_b64 v[102:103], 1, v[182:183]
	v_pk_mul_f32 v[68:69], v[68:69], v[66:67]
	s_mov_b64 s[4:5], 0x4600c00
	v_add_f32_e32 v105, v68, v69
	v_lshl_add_u64 v[68:69], s[50:51], 0, v[0:1]
	v_lshl_add_u64 v[70:71], v[68:69], 0, s[0:1]
	v_lshlrev_b32_e32 v0, 11, v202
	v_lshl_add_u64 v[70:71], v[70:71], 0, v[102:103]
	v_sub_co_u32_e32 v72, vcc, 0, v0
	v_lshl_add_u64 v[106:107], v[70:71], 0, s[4:5]
	s_nop 0
	v_subb_co_u32_e64 v73, s[4:5], 0, 0, vcc
	v_lshl_add_u64 v[68:69], v[68:69], 0, v[72:73]
	v_lshl_add_u64 v[68:69], v[68:69], 0, s[0:1]
	s_mov_b32 s0, 0x4600000
	v_add_co_u32_e32 v70, vcc, s0, v70
	v_div_scale_f32 v0, s[0:1], v105, v105, 1.0
	s_nop 0
	v_addc_co_u32_e32 v71, vcc, 0, v71, vcc
	global_load_dwordx2 v[72:73], v[70:71], off offset:3072
	global_load_dwordx2 v[100:101], v[106:107], off offset:16
	global_load_dwordx2 v[98:99], v[106:107], off offset:32
	global_load_dwordx2 v[96:97], v[106:107], off offset:48
	global_load_dwordx2 v[94:95], v[106:107], off offset:64
	global_load_dwordx2 v[92:93], v[106:107], off offset:80
	global_load_dwordx2 v[90:91], v[106:107], off offset:96
	global_load_dwordx2 v[88:89], v[106:107], off offset:112
	global_load_dwordx2 v[86:87], v[106:107], off offset:128
	global_load_dwordx2 v[84:85], v[106:107], off offset:144
	global_load_dwordx2 v[82:83], v[106:107], off offset:160
	global_load_dwordx2 v[80:81], v[106:107], off offset:176
	global_load_dwordx2 v[78:79], v[106:107], off offset:192
	global_load_dwordx2 v[76:77], v[106:107], off offset:208
	global_load_dwordx2 v[74:75], v[106:107], off offset:224
	global_load_dwordx2 v[70:71], v[106:107], off offset:240
	v_rcp_f32_e32 v106, v0
	v_lshl_add_u64 v[102:103], v[68:69], 0, v[102:103]
	s_mov_b64 s[0:1], 0xae00400
	v_lshl_add_u64 v[68:69], v[102:103], 0, s[0:1]
	v_fma_f32 v107, -v0, v106, 1.0
	v_fmac_f32_e32 v106, v107, v106
	v_div_scale_f32 v107, vcc, 1.0, v105, 1.0
	v_mul_f32_e32 v108, v107, v106
	v_fma_f32 v109, -v0, v108, v107
	v_fmac_f32_e32 v108, v109, v106
	v_fma_f32 v0, -v0, v108, v107
	v_div_fmas_f32 v0, v0, v106, v108
	ds_read2st64_b32 v[106:107], v104 offset1:1
	v_div_fixup_f32 v0, v0, v105, 1.0
	s_waitcnt vmcnt(15)
	v_lshlrev_b32_e32 v105, 16, v72
	v_and_b32_e32 v110, 0xffff0000, v72
	v_mul_f32_e32 v72, 0xbfb8aa3b, v105
	v_exp_f32_e32 v108, v72
	v_mov_b32_e32 v72, v67
	s_waitcnt lgkmcnt(0)
	v_pk_mul_f32 v[106:107], v[72:73], v[106:107] op_sel_hi:[0,1]
	v_pk_fma_f32 v[50:51], v[50:51], v[66:67], v[106:107] op_sel_hi:[1,0,1]
	v_mul_f32_e32 v67, 0xbfb8aa3b, v110
	v_exp_f32_e32 v109, v67
	v_pk_mul_f32 v[50:51], v[0:1], v[50:51] op_sel_hi:[0,1]
	v_pk_add_f32 v[106:107], v[108:109], 1.0 op_sel_hi:[1,0]
	s_nop 0
	v_rcp_f32_e32 v108, v107
	s_nop 0
	v_mul_f32_e32 v107, v110, v108
	v_rcp_f32_e32 v108, v106
	s_nop 0
	v_mul_f32_e32 v106, v105, v108
	v_lshlrev_b32_e32 v67, 16, v73
	v_pk_mul_f32 v[50:51], v[106:107], v[50:51]
	ds_read2st64_b32 v[106:107], v104 offset0:2 offset1:3
	v_and_b32_e32 v73, 0xffff0000, v73
	v_mul_f32_e32 v105, 0xbfb8aa3b, v67
	v_exp_f32_e32 v108, v105
	v_mul_f32_e32 v105, 0xbfb8aa3b, v73
	v_exp_f32_e32 v109, v105
	s_waitcnt lgkmcnt(0)
	v_pk_mul_f32 v[106:107], v[72:73], v[106:107] op_sel_hi:[0,1]
	v_pk_fma_f32 v[52:53], v[52:53], v[66:67], v[106:107] op_sel_hi:[1,0,1]
	v_cvt_pk_bf16_f32 v116, v50, v51
	v_pk_add_f32 v[106:107], v[108:109], 1.0 op_sel_hi:[1,0]
	v_pk_mul_f32 v[52:53], v[0:1], v[52:53] op_sel_hi:[0,1]
	v_rcp_f32_e32 v108, v107
	s_nop 0
	v_mul_f32_e32 v107, v73, v108
	v_div_scale_f32 v73, s[0:1], v106, v106, v67
	v_rcp_f32_e32 v105, v73
	s_mov_b32 s0, 0xae00000
	v_fma_f32 v108, -v73, v105, 1.0
	v_fmac_f32_e32 v105, v108, v105
	v_div_scale_f32 v108, vcc, v67, v106, v67
	v_mul_f32_e32 v109, v108, v105
	v_fma_f32 v110, -v73, v109, v108
	v_fmac_f32_e32 v109, v110, v105
	v_fma_f32 v73, -v73, v109, v108
	v_div_fmas_f32 v73, v73, v105, v109
	v_div_fixup_f32 v106, v73, v106, v67
	v_pk_mul_f32 v[52:53], v[106:107], v[52:53]
	s_waitcnt vmcnt(14)
	v_lshlrev_b32_e32 v67, 16, v100
	v_cvt_pk_bf16_f32 v117, v52, v53
	v_add_co_u32_e32 v52, vcc, s0, v102
	v_and_b32_e32 v73, 0xffff0000, v100
	s_nop 0
	v_addc_co_u32_e32 v53, vcc, 0, v103, vcc
	ds_read2st64_b32 v[50:51], v104 offset0:4 offset1:5
	v_mul_f32_e32 v52, 0xbfb8aa3b, v67
	v_mul_f32_e32 v53, 0xbfb8aa3b, v73
	v_exp_f32_e32 v52, v52
	v_exp_f32_e32 v53, v53
	s_waitcnt lgkmcnt(0)
	v_pk_mul_f32 v[50:51], v[72:73], v[50:51] op_sel_hi:[0,1]
	v_pk_fma_f32 v[50:51], v[54:55], v[66:67], v[50:51] op_sel_hi:[1,0,1]
	v_pk_add_f32 v[52:53], v[52:53], 1.0 op_sel_hi:[1,0]
	s_nop 0
	v_div_scale_f32 v54, s[0:1], v53, v53, v73
	v_rcp_f32_e32 v55, v54
	v_pk_mul_f32 v[50:51], v[0:1], v[50:51] op_sel_hi:[0,1]
	v_fma_f32 v100, -v54, v55, 1.0
	v_fmac_f32_e32 v55, v100, v55
	v_div_scale_f32 v100, vcc, v73, v53, v73
	v_mul_f32_e32 v102, v100, v55
	v_fma_f32 v103, -v54, v102, v100
	v_fmac_f32_e32 v102, v103, v55
	v_fma_f32 v54, -v54, v102, v100
	v_div_fmas_f32 v54, v54, v55, v102
	v_div_fixup_f32 v53, v54, v53, v73
	v_rcp_f32_e32 v55, v52
	s_nop 0
	v_mul_f32_e32 v52, v67, v55
	v_lshlrev_b32_e32 v67, 16, v101
	v_and_b32_e32 v73, 0xffff0000, v101
	v_pk_mul_f32 v[50:51], v[52:53], v[50:51]
	ds_read2st64_b32 v[52:53], v104 offset0:6 offset1:7
	v_mul_f32_e32 v54, 0xbfb8aa3b, v67
	v_mul_f32_e32 v55, 0xbfb8aa3b, v73
	v_exp_f32_e32 v54, v54
	v_exp_f32_e32 v55, v55
	s_waitcnt lgkmcnt(0)
; DI unsigned pk2(float lo, float hi) { f32x2 v = {lo, hi}; return __builtin_bit_cast(unsigned, __builtin_convertvector(v, bf2_t)); }
; DI float bflo(unsigned w) { return __uint_as_float(w << 16); }
; DI float bfhi(unsigned w) { return __uint_as_float(w & 0xffff0000u); }
; DI void attn_unit(const Params& p, int b, int h, int qb, LAS unsigned char* lds, int tid, int lane, int wave) {
;     ...
;             for (int q = 0; q < 4; ++q) gw[i][q] = *(const u32x2*)(gp + i * 32 + q * 8);
; #pragma unroll
;         for (int i = 0; i < 4; ++i)
; #pragma unroll
;             for (int q = 0; q < 4; ++q) {
;                 float gv[4] = {bflo(gw[i][q].x), bfhi(gw[i][q].x), bflo(gw[i][q].y), bfhi(gw[i][q].y)}; float ov[4];
; #pragma unroll
;                 for (int e = 0; e < 4; ++e) { const float val = (o[i][q * 4 + e] * a0 + MB[(i * 16 + q * 4 + e) * 64] * a1) * inv; ov[e] = val * (gv[e] / (1.f + __expf(-gv[e]))); }
;                 *(u32x2*)(op + i * 32 + q * 8) = (u32x2){pk2(ov[0], ov[1]), pk2(ov[2], ov[3])};
	v_pk_mul_f32 v[52:53], v[72:73], v[52:53] op_sel_hi:[0,1]
	v_pk_fma_f32 v[52:53], v[56:57], v[66:67], v[52:53] op_sel_hi:[1,0,1]
	v_cvt_pk_bf16_f32 v118, v50, v51
	v_pk_add_f32 v[54:55], v[54:55], 1.0 op_sel_hi:[1,0]
	v_pk_mul_f32 v[52:53], v[0:1], v[52:53] op_sel_hi:[0,1]
	v_rcp_f32_e32 v57, v55
	s_nop 0
	v_mul_f32_e32 v55, v73, v57
	v_rcp_f32_e32 v57, v54
	s_nop 0
	v_mul_f32_e32 v54, v67, v57
	v_pk_mul_f32 v[52:53], v[54:55], v[52:53]
	s_waitcnt vmcnt(13)
	v_lshlrev_b32_e32 v54, 16, v98
	v_and_b32_e32 v55, 0xffff0000, v98
	v_cvt_pk_bf16_f32 v119, v52, v53
	v_mul_f32_e32 v52, 0xbfb8aa3b, v54
	v_mul_f32_e32 v53, 0xbfb8aa3b, v55
	v_exp_f32_e32 v52, v52
	v_exp_f32_e32 v53, v53
	v_lshlrev_b32_e32 v150, 1, v182
	v_mov_b32_e32 v151, 0
	v_lshl_add_u64 v[148:149], v[150:151], 0, v[68:69]
	s_nop 1
	v_permlane32_swap_b32_e32 v116, v118
	v_permlane32_swap_b32_e32 v117, v119
	global_store_dwordx4 v[148:149], v[116:119], off
	ds_read2st64_b32 v[50:51], v104 offset0:8 offset1:9
	v_pk_add_f32 v[52:53], v[52:53], 1.0 op_sel_hi:[1,0]
	s_nop 0
	v_div_scale_f32 v56, s[0:1], v53, v53, v55
	v_rcp_f32_e32 v57, v56
	s_waitcnt lgkmcnt(0)
	v_pk_mul_f32 v[50:51], v[72:73], v[50:51] op_sel_hi:[0,1]
	v_pk_fma_f32 v[50:51], v[58:59], v[66:67], v[50:51] op_sel_hi:[1,0,1]
	v_fma_f32 v58, -v56, v57, 1.0
	v_fmac_f32_e32 v57, v58, v57
	v_div_scale_f32 v58, vcc, v55, v53, v55
	v_mul_f32_e32 v59, v58, v57
	v_fma_f32 v67, -v56, v59, v58
	v_fmac_f32_e32 v59, v67, v57
	v_fma_f32 v56, -v56, v59, v58
	v_div_fmas_f32 v56, v56, v57, v59
	v_div_fixup_f32 v53, v56, v53, v55
	v_div_scale_f32 v55, s[0:1], v52, v52, v54
	v_rcp_f32_e32 v56, v55
	v_pk_mul_f32 v[50:51], v[0:1], v[50:51] op_sel_hi:[0,1]
	v_fma_f32 v57, -v55, v56, 1.0
	v_fmac_f32_e32 v56, v57, v56
	v_div_scale_f32 v57, vcc, v54, v52, v54
	v_mul_f32_e32 v58, v57, v56
	v_fma_f32 v59, -v55, v58, v57
	v_fmac_f32_e32 v58, v59, v56
	v_fma_f32 v55, -v55, v58, v57
	v_div_fmas_f32 v55, v55, v56, v58
	v_lshlrev_b32_e32 v56, 16, v99
	v_and_b32_e32 v57, 0xffff0000, v99
	v_div_fixup_f32 v52, v55, v52, v54
	v_mul_f32_e32 v54, 0xbfb8aa3b, v56
	v_mul_f32_e32 v55, 0xbfb8aa3b, v57
	v_exp_f32_e32 v54, v54
	v_exp_f32_e32 v55, v55
	v_pk_mul_f32 v[50:51], v[52:53], v[50:51]
	ds_read2st64_b32 v[52:53], v104 offset0:10 offset1:11
	v_cvt_pk_bf16_f32 v120, v50, v51
	v_pk_add_f32 v[54:55], v[54:55], 1.0 op_sel_hi:[1,0]
	s_waitcnt lgkmcnt(0)
	v_pk_mul_f32 v[52:53], v[72:73], v[52:53] op_sel_hi:[0,1]
	v_div_scale_f32 v58, s[0:1], v55, v55, v57
	v_rcp_f32_e32 v59, v58
	v_pk_fma_f32 v[52:53], v[60:61], v[66:67], v[52:53] op_sel_hi:[1,0,1]
	v_fma_f32 v60, -v58, v59, 1.0
	v_fmac_f32_e32 v59, v60, v59
	v_div_scale_f32 v60, vcc, v57, v55, v57
	v_mul_f32_e32 v61, v60, v59
	v_fma_f32 v67, -v58, v61, v60
	v_fmac_f32_e32 v61, v67, v59
	v_fma_f32 v58, -v58, v61, v60
	v_div_fmas_f32 v58, v58, v59, v61
	v_div_fixup_f32 v55, v58, v55, v57
	v_div_scale_f32 v57, s[0:1], v54, v54, v56
	v_rcp_f32_e32 v58, v57
	v_pk_mul_f32 v[52:53], v[0:1], v[52:53] op_sel_hi:[0,1]
	v_fma_f32 v59, -v57, v58, 1.0
	v_fmac_f32_e32 v58, v59, v58
	v_div_scale_f32 v59, vcc, v56, v54, v56
	v_mul_f32_e32 v60, v59, v58
	v_fma_f32 v61, -v57, v60, v59
	v_fmac_f32_e32 v60, v61, v58
	v_fma_f32 v57, -v57, v60, v59
	v_div_fmas_f32 v57, v57, v58, v60
	v_div_fixup_f32 v54, v57, v54, v56
	v_pk_mul_f32 v[52:53], v[54:55], v[52:53]
	s_waitcnt vmcnt(13)
	v_lshlrev_b32_e32 v54, 16, v96
	v_and_b32_e32 v55, 0xffff0000, v96
	v_cvt_pk_bf16_f32 v121, v52, v53
	v_mul_f32_e32 v52, 0xbfb8aa3b, v54
	v_mul_f32_e32 v53, 0xbfb8aa3b, v55
	v_exp_f32_e32 v52, v52
	v_exp_f32_e32 v53, v53
	ds_read2st64_b32 v[50:51], v104 offset0:12 offset1:13
	v_pk_add_f32 v[52:53], v[52:53], 1.0 op_sel_hi:[1,0]
	s_nop 0
	v_div_scale_f32 v56, s[0:1], v53, v53, v55
	v_rcp_f32_e32 v57, v56
	s_waitcnt lgkmcnt(0)
	v_pk_mul_f32 v[50:51], v[72:73], v[50:51] op_sel_hi:[0,1]
	v_pk_fma_f32 v[50:51], v[62:63], v[66:67], v[50:51] op_sel_hi:[1,0,1]
	v_fma_f32 v58, -v56, v57, 1.0
	v_fmac_f32_e32 v57, v58, v57
	v_div_scale_f32 v58, vcc, v55, v53, v55
	v_mul_f32_e32 v59, v58, v57
	v_fma_f32 v60, -v56, v59, v58
	v_fmac_f32_e32 v59, v60, v57
	v_fma_f32 v56, -v56, v59, v58
	v_div_fmas_f32 v56, v56, v57, v59
	v_div_fixup_f32 v53, v56, v53, v55
	v_div_scale_f32 v55, s[0:1], v52, v52, v54
	v_rcp_f32_e32 v56, v55
	v_pk_mul_f32 v[50:51], v[0:1], v[50:51] op_sel_hi:[0,1]
	v_fma_f32 v57, -v55, v56, 1.0
	v_fmac_f32_e32 v56, v57, v56
	v_div_scale_f32 v57, vcc, v54, v52, v54
	v_mul_f32_e32 v58, v57, v56
	v_fma_f32 v59, -v55, v58, v57
	v_fmac_f32_e32 v58, v59, v56
	v_fma_f32 v55, -v55, v58, v57
	v_div_fmas_f32 v55, v55, v56, v58
	v_lshlrev_b32_e32 v56, 16, v97
	v_and_b32_e32 v57, 0xffff0000, v97
	v_div_fixup_f32 v52, v55, v52, v54
	v_mul_f32_e32 v54, 0xbfb8aa3b, v56
	v_mul_f32_e32 v55, 0xbfb8aa3b, v57
	v_exp_f32_e32 v54, v54
	v_exp_f32_e32 v55, v55
	v_pk_mul_f32 v[50:51], v[52:53], v[50:51]
	ds_read2st64_b32 v[52:53], v104 offset0:14 offset1:15
	v_cvt_pk_bf16_f32 v122, v50, v51
	v_pk_add_f32 v[54:55], v[54:55], 1.0 op_sel_hi:[1,0]
	s_waitcnt lgkmcnt(0)
	v_pk_mul_f32 v[52:53], v[72:73], v[52:53] op_sel_hi:[0,1]
	v_div_scale_f32 v58, s[0:1], v55, v55, v57
	v_rcp_f32_e32 v59, v58
	v_pk_fma_f32 v[52:53], v[64:65], v[66:67], v[52:53] op_sel_hi:[1,0,1]
	v_fma_f32 v60, -v58, v59, 1.0
	v_fmac_f32_e32 v59, v60, v59
	v_div_scale_f32 v60, vcc, v57, v55, v57
	v_mul_f32_e32 v61, v60, v59
	v_fma_f32 v62, -v58, v61, v60
	v_fmac_f32_e32 v61, v62, v59
	v_fma_f32 v58, -v58, v61, v60
	v_div_fmas_f32 v58, v58, v59, v61
	v_div_fixup_f32 v55, v58, v55, v57
	v_div_scale_f32 v57, s[0:1], v54, v54, v56
	v_rcp_f32_e32 v58, v57
	v_pk_mul_f32 v[52:53], v[0:1], v[52:53] op_sel_hi:[0,1]
	v_fma_f32 v59, -v57, v58, 1.0
	v_fmac_f32_e32 v58, v59, v58
	v_div_scale_f32 v59, vcc, v56, v54, v56
	v_mul_f32_e32 v60, v59, v58
	v_fma_f32 v61, -v57, v60, v59
	v_fmac_f32_e32 v60, v61, v58
	v_fma_f32 v57, -v57, v60, v59
	v_div_fmas_f32 v57, v57, v58, v60
	v_div_fixup_f32 v54, v57, v54, v56
	v_pk_mul_f32 v[52:53], v[54:55], v[52:53]
	s_waitcnt vmcnt(12)
; DI unsigned pk2(float lo, float hi) { f32x2 v = {lo, hi}; return __builtin_bit_cast(unsigned, __builtin_convertvector(v, bf2_t)); }
; DI float bflo(unsigned w) { return __uint_as_float(w << 16); }
; DI float bfhi(unsigned w) { return __uint_as_float(w & 0xffff0000u); }
; DI void attn_unit(const Params& p, int b, int h, int qb, LAS unsigned char* lds, int tid, int lane, int wave) {
;     ...
;             for (int q = 0; q < 4; ++q) gw[i][q] = *(const u32x2*)(gp + i * 32 + q * 8);
; #pragma unroll
;         for (int i = 0; i < 4; ++i)
; #pragma unroll
;             for (int q = 0; q < 4; ++q) {
;                 float gv[4] = {bflo(gw[i][q].x), bfhi(gw[i][q].x), bflo(gw[i][q].y), bfhi(gw[i][q].y)}; float ov[4];
; #pragma unroll
;                 for (int e = 0; e < 4; ++e) { const float val = (o[i][q * 4 + e] * a0 + MB[(i * 16 + q * 4 + e) * 64] * a1) * inv; ov[e] = val * (gv[e] / (1.f + __expf(-gv[e]))); }
;                 *(u32x2*)(op + i * 32 + q * 8) = (u32x2){pk2(ov[0], ov[1]), pk2(ov[2], ov[3])};
	v_lshlrev_b32_e32 v54, 16, v94
	v_cvt_pk_bf16_f32 v123, v52, v53
	s_nop 1
	v_permlane32_swap_b32_e32 v120, v122
	v_permlane32_swap_b32_e32 v121, v123
	global_store_dwordx4 v[148:149], v[120:123], off offset:32
	ds_read2st64_b32 v[50:51], v104 offset0:16 offset1:17
	v_and_b32_e32 v55, 0xffff0000, v94
	v_mul_f32_e32 v52, 0xbfb8aa3b, v54
	v_exp_f32_e32 v52, v52
	s_waitcnt lgkmcnt(0)
	v_pk_mul_f32 v[50:51], v[72:73], v[50:51] op_sel_hi:[0,1]
	v_pk_fma_f32 v[34:35], v[34:35], v[66:67], v[50:51] op_sel_hi:[1,0,1]
	v_mul_f32_e32 v50, 0xbfb8aa3b, v55
	v_exp_f32_e32 v53, v50
	v_pk_mul_f32 v[34:35], v[0:1], v[34:35] op_sel_hi:[0,1]
	v_pk_add_f32 v[50:51], v[52:53], 1.0 op_sel_hi:[1,0]
	s_nop 0
	v_rcp_f32_e32 v53, v51
	s_nop 0
	v_mul_f32_e32 v51, v55, v53
	v_rcp_f32_e32 v53, v50
	s_nop 0
	v_mul_f32_e32 v50, v54, v53
	v_pk_mul_f32 v[34:35], v[50:51], v[34:35]
	ds_read2st64_b32 v[50:51], v104 offset0:18 offset1:19
	v_lshlrev_b32_e32 v54, 16, v95
	v_and_b32_e32 v55, 0xffff0000, v95
	v_mul_f32_e32 v52, 0xbfb8aa3b, v54
	v_exp_f32_e32 v52, v52
	s_waitcnt lgkmcnt(0)
	v_pk_mul_f32 v[50:51], v[72:73], v[50:51] op_sel_hi:[0,1]
	v_pk_fma_f32 v[36:37], v[36:37], v[66:67], v[50:51] op_sel_hi:[1,0,1]
	v_mul_f32_e32 v50, 0xbfb8aa3b, v55
	v_exp_f32_e32 v53, v50
	v_pk_mul_f32 v[36:37], v[0:1], v[36:37] op_sel_hi:[0,1]
	v_cvt_pk_bf16_f32 v124, v34, v35
	v_pk_add_f32 v[50:51], v[52:53], 1.0 op_sel_hi:[1,0]
	s_nop 0
	v_rcp_f32_e32 v53, v51
	s_nop 0
	v_mul_f32_e32 v51, v55, v53
	v_rcp_f32_e32 v53, v50
	s_nop 0
	v_mul_f32_e32 v50, v54, v53
	v_pk_mul_f32 v[36:37], v[50:51], v[36:37]
	s_waitcnt vmcnt(12)
	v_lshlrev_b32_e32 v50, 16, v92
	v_cvt_pk_bf16_f32 v125, v36, v37
	v_and_b32_e32 v51, 0xffff0000, v92
	ds_read2st64_b32 v[34:35], v104 offset0:20 offset1:21
	v_mul_f32_e32 v36, 0xbfb8aa3b, v50
	v_mul_f32_e32 v37, 0xbfb8aa3b, v51
	v_exp_f32_e32 v36, v36
	v_exp_f32_e32 v37, v37
	s_waitcnt lgkmcnt(0)
	v_pk_mul_f32 v[34:35], v[72:73], v[34:35] op_sel_hi:[0,1]
	v_pk_fma_f32 v[34:35], v[38:39], v[66:67], v[34:35] op_sel_hi:[1,0,1]
	v_pk_add_f32 v[36:37], v[36:37], 1.0 op_sel_hi:[1,0]
	s_nop 0
	v_div_scale_f32 v38, s[0:1], v37, v37, v51
	v_rcp_f32_e32 v39, v38
	v_pk_mul_f32 v[34:35], v[0:1], v[34:35] op_sel_hi:[0,1]
	v_fma_f32 v52, -v38, v39, 1.0
	v_fmac_f32_e32 v39, v52, v39
	v_div_scale_f32 v52, vcc, v51, v37, v51
	v_mul_f32_e32 v53, v52, v39
	v_fma_f32 v54, -v38, v53, v52
	v_fmac_f32_e32 v53, v54, v39
	v_fma_f32 v38, -v38, v53, v52
	v_div_fmas_f32 v38, v38, v39, v53
	v_div_fixup_f32 v37, v38, v37, v51
	v_rcp_f32_e32 v39, v36
	s_nop 0
	v_mul_f32_e32 v36, v50, v39
	v_lshlrev_b32_e32 v50, 16, v93
	v_and_b32_e32 v51, 0xffff0000, v93
	v_pk_mul_f32 v[34:35], v[36:37], v[34:35]
	ds_read2st64_b32 v[36:37], v104 offset0:22 offset1:23
	v_mul_f32_e32 v38, 0xbfb8aa3b, v50
	v_mul_f32_e32 v39, 0xbfb8aa3b, v51
	v_exp_f32_e32 v38, v38
	v_exp_f32_e32 v39, v39
	s_waitcnt lgkmcnt(0)
	v_pk_mul_f32 v[36:37], v[72:73], v[36:37] op_sel_hi:[0,1]
	v_pk_fma_f32 v[36:37], v[40:41], v[66:67], v[36:37] op_sel_hi:[1,0,1]
	v_cvt_pk_bf16_f32 v126, v34, v35
	v_pk_add_f32 v[38:39], v[38:39], 1.0 op_sel_hi:[1,0]
	v_pk_mul_f32 v[36:37], v[0:1], v[36:37] op_sel_hi:[0,1]
	v_rcp_f32_e32 v41, v39
	s_nop 0
	v_mul_f32_e32 v39, v51, v41
	v_rcp_f32_e32 v41, v38
	s_nop 0
	v_mul_f32_e32 v38, v50, v41
	v_pk_mul_f32 v[36:37], v[38:39], v[36:37]
	s_waitcnt vmcnt(11)
	v_lshlrev_b32_e32 v38, 16, v90
	v_and_b32_e32 v39, 0xffff0000, v90
	v_cvt_pk_bf16_f32 v127, v36, v37
	v_mul_f32_e32 v36, 0xbfb8aa3b, v38
	v_mul_f32_e32 v37, 0xbfb8aa3b, v39
	v_exp_f32_e32 v36, v36
	v_exp_f32_e32 v37, v37
	s_nop 1
	v_permlane32_swap_b32_e32 v124, v126
	v_permlane32_swap_b32_e32 v125, v127
	global_store_dwordx4 v[148:149], v[124:127], off offset:64
	ds_read2st64_b32 v[34:35], v104 offset0:24 offset1:25
	v_pk_add_f32 v[36:37], v[36:37], 1.0 op_sel_hi:[1,0]
	s_nop 0
	v_div_scale_f32 v40, s[0:1], v37, v37, v39
	v_rcp_f32_e32 v41, v40
	s_waitcnt lgkmcnt(0)
	v_pk_mul_f32 v[34:35], v[72:73], v[34:35] op_sel_hi:[0,1]
	v_pk_fma_f32 v[34:35], v[42:43], v[66:67], v[34:35] op_sel_hi:[1,0,1]
	v_fma_f32 v42, -v40, v41, 1.0
	v_fmac_f32_e32 v41, v42, v41
	v_div_scale_f32 v42, vcc, v39, v37, v39
	v_mul_f32_e32 v43, v42, v41
	v_fma_f32 v50, -v40, v43, v42
	v_fmac_f32_e32 v43, v50, v41
	v_fma_f32 v40, -v40, v43, v42
	v_div_fmas_f32 v40, v40, v41, v43
	v_div_fixup_f32 v37, v40, v37, v39
	v_div_scale_f32 v39, s[0:1], v36, v36, v38
	v_rcp_f32_e32 v40, v39
	v_pk_mul_f32 v[34:35], v[0:1], v[34:35] op_sel_hi:[0,1]
	v_fma_f32 v41, -v39, v40, 1.0
	v_fmac_f32_e32 v40, v41, v40
	v_div_scale_f32 v41, vcc, v38, v36, v38
	v_mul_f32_e32 v42, v41, v40
	v_fma_f32 v43, -v39, v42, v41
	v_fmac_f32_e32 v42, v43, v40
	v_fma_f32 v39, -v39, v42, v41
	v_div_fmas_f32 v39, v39, v40, v42
	v_lshlrev_b32_e32 v40, 16, v91
	v_and_b32_e32 v41, 0xffff0000, v91
	v_div_fixup_f32 v36, v39, v36, v38
	v_mul_f32_e32 v38, 0xbfb8aa3b, v40
	v_mul_f32_e32 v39, 0xbfb8aa3b, v41
	v_exp_f32_e32 v38, v38
	v_exp_f32_e32 v39, v39
	v_pk_mul_f32 v[34:35], v[36:37], v[34:35]
	ds_read2st64_b32 v[36:37], v104 offset0:26 offset1:27
	v_cvt_pk_bf16_f32 v128, v34, v35
	v_pk_add_f32 v[38:39], v[38:39], 1.0 op_sel_hi:[1,0]
	s_waitcnt lgkmcnt(0)
; DI unsigned pk2(float lo, float hi) { f32x2 v = {lo, hi}; return __builtin_bit_cast(unsigned, __builtin_convertvector(v, bf2_t)); }
; DI float bflo(unsigned w) { return __uint_as_float(w << 16); }
; DI float bfhi(unsigned w) { return __uint_as_float(w & 0xffff0000u); }
; DI void attn_unit(const Params& p, int b, int h, int qb, LAS unsigned char* lds, int tid, int lane, int wave) {
;     ...
;             for (int q = 0; q < 4; ++q) gw[i][q] = *(const u32x2*)(gp + i * 32 + q * 8);
; #pragma unroll
;         for (int i = 0; i < 4; ++i)
; #pragma unroll
;             for (int q = 0; q < 4; ++q) {
;                 float gv[4] = {bflo(gw[i][q].x), bfhi(gw[i][q].x), bflo(gw[i][q].y), bfhi(gw[i][q].y)}; float ov[4];
; #pragma unroll
;                 for (int e = 0; e < 4; ++e) { const float val = (o[i][q * 4 + e] * a0 + MB[(i * 16 + q * 4 + e) * 64] * a1) * inv; ov[e] = val * (gv[e] / (1.f + __expf(-gv[e]))); }
;                 *(u32x2*)(op + i * 32 + q * 8) = (u32x2){pk2(ov[0], ov[1]), pk2(ov[2], ov[3])};
	v_pk_mul_f32 v[36:37], v[72:73], v[36:37] op_sel_hi:[0,1]
	v_div_scale_f32 v42, s[0:1], v39, v39, v41
	v_rcp_f32_e32 v43, v42
	v_pk_fma_f32 v[36:37], v[44:45], v[66:67], v[36:37] op_sel_hi:[1,0,1]
	v_fma_f32 v44, -v42, v43, 1.0
	v_fmac_f32_e32 v43, v44, v43
	v_div_scale_f32 v44, vcc, v41, v39, v41
	v_mul_f32_e32 v45, v44, v43
	v_fma_f32 v50, -v42, v45, v44
	v_fmac_f32_e32 v45, v50, v43
	v_fma_f32 v42, -v42, v45, v44
	v_div_fmas_f32 v42, v42, v43, v45
	v_div_fixup_f32 v39, v42, v39, v41
	v_div_scale_f32 v41, s[0:1], v38, v38, v40
	v_rcp_f32_e32 v42, v41
	v_pk_mul_f32 v[36:37], v[0:1], v[36:37] op_sel_hi:[0,1]
	v_fma_f32 v43, -v41, v42, 1.0
	v_fmac_f32_e32 v42, v43, v42
	v_div_scale_f32 v43, vcc, v40, v38, v40
	v_mul_f32_e32 v44, v43, v42
	v_fma_f32 v45, -v41, v44, v43
	v_fmac_f32_e32 v44, v45, v42
	v_fma_f32 v41, -v41, v44, v43
	v_div_fmas_f32 v41, v41, v42, v44
	v_div_fixup_f32 v38, v41, v38, v40
	v_pk_mul_f32 v[36:37], v[38:39], v[36:37]
	s_waitcnt vmcnt(11)
	v_lshlrev_b32_e32 v38, 16, v88
	v_and_b32_e32 v39, 0xffff0000, v88
	v_cvt_pk_bf16_f32 v129, v36, v37
	v_mul_f32_e32 v36, 0xbfb8aa3b, v38
	v_mul_f32_e32 v37, 0xbfb8aa3b, v39
	v_exp_f32_e32 v36, v36
	v_exp_f32_e32 v37, v37
	ds_read2st64_b32 v[34:35], v104 offset0:28 offset1:29
	v_pk_add_f32 v[36:37], v[36:37], 1.0 op_sel_hi:[1,0]
	s_nop 0
	v_div_scale_f32 v40, s[0:1], v37, v37, v39
	v_rcp_f32_e32 v41, v40
	s_waitcnt lgkmcnt(0)
	v_pk_mul_f32 v[34:35], v[72:73], v[34:35] op_sel_hi:[0,1]
	v_pk_fma_f32 v[34:35], v[46:47], v[66:67], v[34:35] op_sel_hi:[1,0,1]
	v_fma_f32 v42, -v40, v41, 1.0
	v_fmac_f32_e32 v41, v42, v41
	v_div_scale_f32 v42, vcc, v39, v37, v39
	v_mul_f32_e32 v43, v42, v41
	v_fma_f32 v44, -v40, v43, v42
	v_fmac_f32_e32 v43, v44, v41
	v_fma_f32 v40, -v40, v43, v42
	v_div_fmas_f32 v40, v40, v41, v43
	v_div_fixup_f32 v37, v40, v37, v39
	v_div_scale_f32 v39, s[0:1], v36, v36, v38
	v_rcp_f32_e32 v40, v39
	v_pk_mul_f32 v[34:35], v[0:1], v[34:35] op_sel_hi:[0,1]
	v_fma_f32 v41, -v39, v40, 1.0
	v_fmac_f32_e32 v40, v41, v40
	v_div_scale_f32 v41, vcc, v38, v36, v38
	v_mul_f32_e32 v42, v41, v40
	v_fma_f32 v43, -v39, v42, v41
	v_fmac_f32_e32 v42, v43, v40
	v_fma_f32 v39, -v39, v42, v41
	v_div_fmas_f32 v39, v39, v40, v42
	v_lshlrev_b32_e32 v40, 16, v89
	v_and_b32_e32 v41, 0xffff0000, v89
	v_div_fixup_f32 v36, v39, v36, v38
	v_mul_f32_e32 v38, 0xbfb8aa3b, v40
	v_mul_f32_e32 v39, 0xbfb8aa3b, v41
	v_exp_f32_e32 v38, v38
	v_exp_f32_e32 v39, v39
	v_pk_mul_f32 v[34:35], v[36:37], v[34:35]
	ds_read2st64_b32 v[36:37], v104 offset0:30 offset1:31
	v_cvt_pk_bf16_f32 v130, v34, v35
	v_pk_add_f32 v[38:39], v[38:39], 1.0 op_sel_hi:[1,0]
	s_waitcnt lgkmcnt(0)
	v_pk_mul_f32 v[36:37], v[72:73], v[36:37] op_sel_hi:[0,1]
	v_div_scale_f32 v42, s[0:1], v39, v39, v41
	v_rcp_f32_e32 v43, v42
	v_pk_fma_f32 v[36:37], v[48:49], v[66:67], v[36:37] op_sel_hi:[1,0,1]
	v_fma_f32 v44, -v42, v43, 1.0
	v_fmac_f32_e32 v43, v44, v43
	v_div_scale_f32 v44, vcc, v41, v39, v41
	v_mul_f32_e32 v45, v44, v43
	v_fma_f32 v46, -v42, v45, v44
	v_fmac_f32_e32 v45, v46, v43
	v_fma_f32 v42, -v42, v45, v44
	v_div_fmas_f32 v42, v42, v43, v45
	v_div_fixup_f32 v39, v42, v39, v41
	v_div_scale_f32 v41, s[0:1], v38, v38, v40
	v_rcp_f32_e32 v42, v41
	v_pk_mul_f32 v[36:37], v[0:1], v[36:37] op_sel_hi:[0,1]
	v_fma_f32 v43, -v41, v42, 1.0
	v_fmac_f32_e32 v42, v43, v42
	v_div_scale_f32 v43, vcc, v40, v38, v40
	v_mul_f32_e32 v44, v43, v42
	v_fma_f32 v45, -v41, v44, v43
	v_fmac_f32_e32 v44, v45, v42
	v_fma_f32 v41, -v41, v44, v43
	v_div_fmas_f32 v41, v41, v42, v44
	v_div_fixup_f32 v38, v41, v38, v40
	v_pk_mul_f32 v[36:37], v[38:39], v[36:37]
	s_waitcnt vmcnt(10)
	v_lshlrev_b32_e32 v38, 16, v86
	v_cvt_pk_bf16_f32 v131, v36, v37
	s_nop 1
	v_permlane32_swap_b32_e32 v128, v130
	v_permlane32_swap_b32_e32 v129, v131
	global_store_dwordx4 v[148:149], v[128:131], off offset:96
	ds_read2st64_b32 v[34:35], v104 offset0:32 offset1:33
	v_and_b32_e32 v39, 0xffff0000, v86
	v_mul_f32_e32 v36, 0xbfb8aa3b, v38
	v_exp_f32_e32 v36, v36
	s_waitcnt lgkmcnt(0)
	v_pk_mul_f32 v[34:35], v[72:73], v[34:35] op_sel_hi:[0,1]
	v_pk_fma_f32 v[18:19], v[18:19], v[66:67], v[34:35] op_sel_hi:[1,0,1]
	v_mul_f32_e32 v34, 0xbfb8aa3b, v39
	v_exp_f32_e32 v37, v34
	v_pk_mul_f32 v[18:19], v[0:1], v[18:19] op_sel_hi:[0,1]
	v_pk_add_f32 v[34:35], v[36:37], 1.0 op_sel_hi:[1,0]
	s_nop 0
	v_rcp_f32_e32 v37, v35
	s_nop 0
	v_mul_f32_e32 v35, v39, v37
	v_rcp_f32_e32 v37, v34
	s_nop 0
	v_mul_f32_e32 v34, v38, v37
	v_pk_mul_f32 v[18:19], v[34:35], v[18:19]
	ds_read2st64_b32 v[34:35], v104 offset0:34 offset1:35
	v_lshlrev_b32_e32 v38, 16, v87
	v_and_b32_e32 v39, 0xffff0000, v87
	v_mul_f32_e32 v36, 0xbfb8aa3b, v38
	v_exp_f32_e32 v36, v36
	s_waitcnt lgkmcnt(0)
	v_pk_mul_f32 v[34:35], v[72:73], v[34:35] op_sel_hi:[0,1]
	v_pk_fma_f32 v[20:21], v[20:21], v[66:67], v[34:35] op_sel_hi:[1,0,1]
	v_mul_f32_e32 v34, 0xbfb8aa3b, v39
	v_exp_f32_e32 v37, v34
	v_pk_mul_f32 v[20:21], v[0:1], v[20:21] op_sel_hi:[0,1]
	v_cvt_pk_bf16_f32 v132, v18, v19
	v_pk_add_f32 v[34:35], v[36:37], 1.0 op_sel_hi:[1,0]
	s_nop 0
	v_rcp_f32_e32 v37, v35
	s_nop 0
	v_mul_f32_e32 v35, v39, v37
	v_rcp_f32_e32 v37, v34
	s_nop 0
	v_mul_f32_e32 v34, v38, v37
	v_pk_mul_f32 v[20:21], v[34:35], v[20:21]
	s_waitcnt vmcnt(10)
	v_lshlrev_b32_e32 v34, 16, v84
	v_cvt_pk_bf16_f32 v133, v20, v21
	v_and_b32_e32 v35, 0xffff0000, v84
	ds_read2st64_b32 v[18:19], v104 offset0:36 offset1:37
	v_mul_f32_e32 v20, 0xbfb8aa3b, v34
	v_mul_f32_e32 v21, 0xbfb8aa3b, v35
	v_exp_f32_e32 v20, v20
	v_exp_f32_e32 v21, v21
	s_waitcnt lgkmcnt(0)
; DI unsigned pk2(float lo, float hi) { f32x2 v = {lo, hi}; return __builtin_bit_cast(unsigned, __builtin_convertvector(v, bf2_t)); }
; DI float bflo(unsigned w) { return __uint_as_float(w << 16); }
; DI float bfhi(unsigned w) { return __uint_as_float(w & 0xffff0000u); }
; DI void attn_unit(const Params& p, int b, int h, int qb, LAS unsigned char* lds, int tid, int lane, int wave) {
;     ...
; #pragma unroll
;         for (int i = 0; i < 4; ++i)
; #pragma unroll
;             for (int q = 0; q < 4; ++q) {
;                 float gv[4] = {bflo(gw[i][q].x), bfhi(gw[i][q].x), bflo(gw[i][q].y), bfhi(gw[i][q].y)}; float ov[4];
; #pragma unroll
;                 for (int e = 0; e < 4; ++e) { const float val = (o[i][q * 4 + e] * a0 + MB[(i * 16 + q * 4 + e) * 64] * a1) * inv; ov[e] = val * (gv[e] / (1.f + __expf(-gv[e]))); }
;                 *(u32x2*)(op + i * 32 + q * 8) = (u32x2){pk2(ov[0], ov[1]), pk2(ov[2], ov[3])};
;             }
	v_pk_mul_f32 v[18:19], v[72:73], v[18:19] op_sel_hi:[0,1]
	v_pk_fma_f32 v[18:19], v[22:23], v[66:67], v[18:19] op_sel_hi:[1,0,1]
	v_pk_add_f32 v[20:21], v[20:21], 1.0 op_sel_hi:[1,0]
	s_nop 0
	v_div_scale_f32 v22, s[0:1], v21, v21, v35
	v_rcp_f32_e32 v23, v22
	v_pk_mul_f32 v[18:19], v[0:1], v[18:19] op_sel_hi:[0,1]
	v_fma_f32 v36, -v22, v23, 1.0
	v_fmac_f32_e32 v23, v36, v23
	v_div_scale_f32 v36, vcc, v35, v21, v35
	v_mul_f32_e32 v37, v36, v23
	v_fma_f32 v38, -v22, v37, v36
	v_fmac_f32_e32 v37, v38, v23
	v_fma_f32 v22, -v22, v37, v36
	v_div_fmas_f32 v22, v22, v23, v37
	v_div_fixup_f32 v21, v22, v21, v35
	v_rcp_f32_e32 v23, v20
	s_nop 0
	v_mul_f32_e32 v20, v34, v23
	v_lshlrev_b32_e32 v34, 16, v85
	v_and_b32_e32 v35, 0xffff0000, v85
	v_pk_mul_f32 v[18:19], v[20:21], v[18:19]
	ds_read2st64_b32 v[20:21], v104 offset0:38 offset1:39
	v_mul_f32_e32 v22, 0xbfb8aa3b, v34
	v_mul_f32_e32 v23, 0xbfb8aa3b, v35
	v_exp_f32_e32 v22, v22
	v_exp_f32_e32 v23, v23
	s_waitcnt lgkmcnt(0)
	v_pk_mul_f32 v[20:21], v[72:73], v[20:21] op_sel_hi:[0,1]
	v_pk_fma_f32 v[20:21], v[24:25], v[66:67], v[20:21] op_sel_hi:[1,0,1]
	v_cvt_pk_bf16_f32 v134, v18, v19
	v_pk_add_f32 v[22:23], v[22:23], 1.0 op_sel_hi:[1,0]
	v_pk_mul_f32 v[20:21], v[0:1], v[20:21] op_sel_hi:[0,1]
	v_rcp_f32_e32 v25, v23
	s_nop 0
	v_mul_f32_e32 v23, v35, v25
	v_rcp_f32_e32 v25, v22
	s_nop 0
	v_mul_f32_e32 v22, v34, v25
	v_pk_mul_f32 v[20:21], v[22:23], v[20:21]
	s_waitcnt vmcnt(9)
	v_lshlrev_b32_e32 v22, 16, v82
	v_and_b32_e32 v23, 0xffff0000, v82
	v_cvt_pk_bf16_f32 v135, v20, v21
	v_mul_f32_e32 v20, 0xbfb8aa3b, v22
	v_mul_f32_e32 v21, 0xbfb8aa3b, v23
	v_exp_f32_e32 v20, v20
	v_exp_f32_e32 v21, v21
	s_nop 1
	v_permlane32_swap_b32_e32 v132, v134
	v_permlane32_swap_b32_e32 v133, v135
	global_store_dwordx4 v[148:149], v[132:135], off offset:128
	ds_read2st64_b32 v[18:19], v104 offset0:40 offset1:41
	v_pk_add_f32 v[20:21], v[20:21], 1.0 op_sel_hi:[1,0]
	s_nop 0
	v_div_scale_f32 v24, s[0:1], v21, v21, v23
	v_rcp_f32_e32 v25, v24
	s_waitcnt lgkmcnt(0)
	v_pk_mul_f32 v[18:19], v[72:73], v[18:19] op_sel_hi:[0,1]
	v_pk_fma_f32 v[18:19], v[26:27], v[66:67], v[18:19] op_sel_hi:[1,0,1]
	v_fma_f32 v26, -v24, v25, 1.0
	v_fmac_f32_e32 v25, v26, v25
	v_div_scale_f32 v26, vcc, v23, v21, v23
	v_mul_f32_e32 v27, v26, v25
	v_fma_f32 v34, -v24, v27, v26
	v_fmac_f32_e32 v27, v34, v25
	v_fma_f32 v24, -v24, v27, v26
	v_div_fmas_f32 v24, v24, v25, v27
	v_div_fixup_f32 v21, v24, v21, v23
	v_div_scale_f32 v23, s[0:1], v20, v20, v22
	v_rcp_f32_e32 v24, v23
	v_pk_mul_f32 v[18:19], v[0:1], v[18:19] op_sel_hi:[0,1]
	v_fma_f32 v25, -v23, v24, 1.0
	v_fmac_f32_e32 v24, v25, v24
	v_div_scale_f32 v25, vcc, v22, v20, v22
	v_mul_f32_e32 v26, v25, v24
	v_fma_f32 v27, -v23, v26, v25
	v_fmac_f32_e32 v26, v27, v24
	v_fma_f32 v23, -v23, v26, v25
	v_div_fmas_f32 v23, v23, v24, v26
	v_lshlrev_b32_e32 v24, 16, v83
	v_and_b32_e32 v25, 0xffff0000, v83
	v_div_fixup_f32 v20, v23, v20, v22
	v_mul_f32_e32 v22, 0xbfb8aa3b, v24
	v_mul_f32_e32 v23, 0xbfb8aa3b, v25
	v_exp_f32_e32 v22, v22
	v_exp_f32_e32 v23, v23
	v_pk_mul_f32 v[18:19], v[20:21], v[18:19]
	ds_read2st64_b32 v[20:21], v104 offset0:42 offset1:43
	v_cvt_pk_bf16_f32 v136, v18, v19
	v_pk_add_f32 v[22:23], v[22:23], 1.0 op_sel_hi:[1,0]
	s_waitcnt lgkmcnt(0)
	v_pk_mul_f32 v[20:21], v[72:73], v[20:21] op_sel_hi:[0,1]
	v_div_scale_f32 v26, s[0:1], v23, v23, v25
	v_rcp_f32_e32 v27, v26
	v_pk_fma_f32 v[20:21], v[28:29], v[66:67], v[20:21] op_sel_hi:[1,0,1]
	v_fma_f32 v28, -v26, v27, 1.0
	v_fmac_f32_e32 v27, v28, v27
	v_div_scale_f32 v28, vcc, v25, v23, v25
	v_mul_f32_e32 v29, v28, v27
	v_fma_f32 v34, -v26, v29, v28
	v_fmac_f32_e32 v29, v34, v27
	v_fma_f32 v26, -v26, v29, v28
	v_div_fmas_f32 v26, v26, v27, v29
	v_div_fixup_f32 v23, v26, v23, v25
	v_div_scale_f32 v25, s[0:1], v22, v22, v24
	v_rcp_f32_e32 v26, v25
	v_pk_mul_f32 v[20:21], v[0:1], v[20:21] op_sel_hi:[0,1]
	v_fma_f32 v27, -v25, v26, 1.0
	v_fmac_f32_e32 v26, v27, v26
	v_div_scale_f32 v27, vcc, v24, v22, v24
	v_mul_f32_e32 v28, v27, v26
	v_fma_f32 v29, -v25, v28, v27
	v_fmac_f32_e32 v28, v29, v26
	v_fma_f32 v25, -v25, v28, v27
	v_div_fmas_f32 v25, v25, v26, v28
	v_div_fixup_f32 v22, v25, v22, v24
	v_pk_mul_f32 v[20:21], v[22:23], v[20:21]
	s_waitcnt vmcnt(9)
	v_lshlrev_b32_e32 v22, 16, v80
	v_and_b32_e32 v23, 0xffff0000, v80
	v_cvt_pk_bf16_f32 v137, v20, v21
	v_mul_f32_e32 v20, 0xbfb8aa3b, v22
	v_mul_f32_e32 v21, 0xbfb8aa3b, v23
	v_exp_f32_e32 v20, v20
	v_exp_f32_e32 v21, v21
	ds_read2st64_b32 v[18:19], v104 offset0:44 offset1:45
	v_pk_add_f32 v[20:21], v[20:21], 1.0 op_sel_hi:[1,0]
	s_nop 0
	v_div_scale_f32 v24, s[0:1], v21, v21, v23
	v_rcp_f32_e32 v25, v24
	s_waitcnt lgkmcnt(0)
	v_pk_mul_f32 v[18:19], v[72:73], v[18:19] op_sel_hi:[0,1]
	v_pk_fma_f32 v[18:19], v[30:31], v[66:67], v[18:19] op_sel_hi:[1,0,1]
	v_fma_f32 v26, -v24, v25, 1.0
	v_fmac_f32_e32 v25, v26, v25
	v_div_scale_f32 v26, vcc, v23, v21, v23
	v_mul_f32_e32 v27, v26, v25
	v_fma_f32 v28, -v24, v27, v26
	v_fmac_f32_e32 v27, v28, v25
	v_fma_f32 v24, -v24, v27, v26
	v_div_fmas_f32 v24, v24, v25, v27
	v_div_fixup_f32 v21, v24, v21, v23
	v_div_scale_f32 v23, s[0:1], v20, v20, v22
	v_rcp_f32_e32 v24, v23
	v_pk_mul_f32 v[18:19], v[0:1], v[18:19] op_sel_hi:[0,1]
	v_fma_f32 v25, -v23, v24, 1.0
	v_fmac_f32_e32 v24, v25, v24
	v_div_scale_f32 v25, vcc, v22, v20, v22
	v_mul_f32_e32 v26, v25, v24
	v_fma_f32 v27, -v23, v26, v25
	v_fmac_f32_e32 v26, v27, v24
	v_fma_f32 v23, -v23, v26, v25
	v_div_fmas_f32 v23, v23, v24, v26
	v_lshlrev_b32_e32 v24, 16, v81
	v_and_b32_e32 v25, 0xffff0000, v81
	v_div_fixup_f32 v20, v23, v20, v22
	v_mul_f32_e32 v22, 0xbfb8aa3b, v24
	v_mul_f32_e32 v23, 0xbfb8aa3b, v25
	v_exp_f32_e32 v22, v22
	v_exp_f32_e32 v23, v23
	v_pk_mul_f32 v[18:19], v[20:21], v[18:19]
	ds_read2st64_b32 v[20:21], v104 offset0:46 offset1:47
	v_cvt_pk_bf16_f32 v138, v18, v19
	v_pk_add_f32 v[22:23], v[22:23], 1.0 op_sel_hi:[1,0]
	s_waitcnt lgkmcnt(0)
; DI unsigned pk2(float lo, float hi) { f32x2 v = {lo, hi}; return __builtin_bit_cast(unsigned, __builtin_convertvector(v, bf2_t)); }
; DI float bflo(unsigned w) { return __uint_as_float(w << 16); }
; DI float bfhi(unsigned w) { return __uint_as_float(w & 0xffff0000u); }
; DI void attn_unit(const Params& p, int b, int h, int qb, LAS unsigned char* lds, int tid, int lane, int wave) {
;     ...
; #pragma unroll
;         for (int i = 0; i < 4; ++i)
; #pragma unroll
;             for (int q = 0; q < 4; ++q) {
;                 float gv[4] = {bflo(gw[i][q].x), bfhi(gw[i][q].x), bflo(gw[i][q].y), bfhi(gw[i][q].y)}; float ov[4];
; #pragma unroll
;                 for (int e = 0; e < 4; ++e) { const float val = (o[i][q * 4 + e] * a0 + MB[(i * 16 + q * 4 + e) * 64] * a1) * inv; ov[e] = val * (gv[e] / (1.f + __expf(-gv[e]))); }
;                 *(u32x2*)(op + i * 32 + q * 8) = (u32x2){pk2(ov[0], ov[1]), pk2(ov[2], ov[3])};
;             }
	v_pk_mul_f32 v[20:21], v[72:73], v[20:21] op_sel_hi:[0,1]
	v_div_scale_f32 v26, s[0:1], v23, v23, v25
	v_rcp_f32_e32 v27, v26
	v_pk_fma_f32 v[20:21], v[32:33], v[66:67], v[20:21] op_sel_hi:[1,0,1]
	v_fma_f32 v28, -v26, v27, 1.0
	v_fmac_f32_e32 v27, v28, v27
	v_div_scale_f32 v28, vcc, v25, v23, v25
	v_mul_f32_e32 v29, v28, v27
	v_fma_f32 v30, -v26, v29, v28
	v_fmac_f32_e32 v29, v30, v27
	v_fma_f32 v26, -v26, v29, v28
	v_div_fmas_f32 v26, v26, v27, v29
	v_div_fixup_f32 v23, v26, v23, v25
	v_div_scale_f32 v25, s[0:1], v22, v22, v24
	v_rcp_f32_e32 v26, v25
	v_pk_mul_f32 v[20:21], v[0:1], v[20:21] op_sel_hi:[0,1]
	v_fma_f32 v27, -v25, v26, 1.0
	v_fmac_f32_e32 v26, v27, v26
	v_div_scale_f32 v27, vcc, v24, v22, v24
	v_mul_f32_e32 v28, v27, v26
	v_fma_f32 v29, -v25, v28, v27
	v_fmac_f32_e32 v28, v29, v26
	v_fma_f32 v25, -v25, v28, v27
	v_div_fmas_f32 v25, v25, v26, v28
	v_div_fixup_f32 v22, v25, v22, v24
	v_pk_mul_f32 v[20:21], v[22:23], v[20:21]
	s_waitcnt vmcnt(8)
	v_lshlrev_b32_e32 v22, 16, v78
	v_cvt_pk_bf16_f32 v139, v20, v21
	s_nop 1
	v_permlane32_swap_b32_e32 v136, v138
	v_permlane32_swap_b32_e32 v137, v139
	global_store_dwordx4 v[148:149], v[136:139], off offset:160
	ds_read2st64_b32 v[18:19], v104 offset0:48 offset1:49
	v_and_b32_e32 v23, 0xffff0000, v78
	v_mul_f32_e32 v20, 0xbfb8aa3b, v22
	v_exp_f32_e32 v20, v20
	s_waitcnt lgkmcnt(0)
	v_pk_mul_f32 v[18:19], v[72:73], v[18:19] op_sel_hi:[0,1]
	v_pk_fma_f32 v[2:3], v[2:3], v[66:67], v[18:19] op_sel_hi:[1,0,1]
	v_mul_f32_e32 v18, 0xbfb8aa3b, v23
	v_exp_f32_e32 v21, v18
	v_pk_mul_f32 v[2:3], v[0:1], v[2:3] op_sel_hi:[0,1]
	v_pk_add_f32 v[18:19], v[20:21], 1.0 op_sel_hi:[1,0]
	s_nop 0
	v_rcp_f32_e32 v21, v19
	s_nop 0
	v_mul_f32_e32 v19, v23, v21
	v_rcp_f32_e32 v21, v18
	s_nop 0
	v_mul_f32_e32 v18, v22, v21
	v_pk_mul_f32 v[2:3], v[18:19], v[2:3]
	ds_read2st64_b32 v[18:19], v104 offset0:50 offset1:51
	v_lshlrev_b32_e32 v22, 16, v79
	v_and_b32_e32 v23, 0xffff0000, v79
	v_mul_f32_e32 v20, 0xbfb8aa3b, v22
	v_exp_f32_e32 v20, v20
	s_waitcnt lgkmcnt(0)
	v_pk_mul_f32 v[18:19], v[72:73], v[18:19] op_sel_hi:[0,1]
	v_pk_fma_f32 v[4:5], v[4:5], v[66:67], v[18:19] op_sel_hi:[1,0,1]
	v_mul_f32_e32 v18, 0xbfb8aa3b, v23
	v_exp_f32_e32 v21, v18
	v_pk_mul_f32 v[4:5], v[0:1], v[4:5] op_sel_hi:[0,1]
	v_cvt_pk_bf16_f32 v140, v2, v3
	v_pk_add_f32 v[18:19], v[20:21], 1.0 op_sel_hi:[1,0]
	s_nop 0
	v_rcp_f32_e32 v21, v19
	s_nop 0
	v_mul_f32_e32 v19, v23, v21
	v_rcp_f32_e32 v21, v18
	s_nop 0
	v_mul_f32_e32 v18, v22, v21
	v_pk_mul_f32 v[4:5], v[18:19], v[4:5]
	s_waitcnt vmcnt(8)
	v_lshlrev_b32_e32 v18, 16, v76
	v_cvt_pk_bf16_f32 v141, v4, v5
	v_and_b32_e32 v19, 0xffff0000, v76
	ds_read2st64_b32 v[2:3], v104 offset0:52 offset1:53
	v_mul_f32_e32 v4, 0xbfb8aa3b, v18
	v_mul_f32_e32 v5, 0xbfb8aa3b, v19
	v_exp_f32_e32 v4, v4
	v_exp_f32_e32 v5, v5
	s_waitcnt lgkmcnt(0)
	v_pk_mul_f32 v[2:3], v[72:73], v[2:3] op_sel_hi:[0,1]
	v_pk_fma_f32 v[2:3], v[6:7], v[66:67], v[2:3] op_sel_hi:[1,0,1]
	v_pk_add_f32 v[4:5], v[4:5], 1.0 op_sel_hi:[1,0]
	s_nop 0
	v_div_scale_f32 v6, s[0:1], v5, v5, v19
	v_rcp_f32_e32 v7, v6
	v_pk_mul_f32 v[2:3], v[0:1], v[2:3] op_sel_hi:[0,1]
	v_fma_f32 v20, -v6, v7, 1.0
	v_fmac_f32_e32 v7, v20, v7
	v_div_scale_f32 v20, vcc, v19, v5, v19
	v_mul_f32_e32 v21, v20, v7
	v_fma_f32 v22, -v6, v21, v20
	v_fmac_f32_e32 v21, v22, v7
	v_fma_f32 v6, -v6, v21, v20
	v_div_fmas_f32 v6, v6, v7, v21
	v_div_fixup_f32 v5, v6, v5, v19
	v_rcp_f32_e32 v7, v4
	s_nop 0
	v_mul_f32_e32 v4, v18, v7
	v_lshlrev_b32_e32 v18, 16, v77
	v_and_b32_e32 v19, 0xffff0000, v77
	v_pk_mul_f32 v[2:3], v[4:5], v[2:3]
	ds_read2st64_b32 v[4:5], v104 offset0:54 offset1:55
	v_mul_f32_e32 v6, 0xbfb8aa3b, v18
	v_mul_f32_e32 v7, 0xbfb8aa3b, v19
	v_exp_f32_e32 v6, v6
	v_exp_f32_e32 v7, v7
	s_waitcnt lgkmcnt(0)
	v_pk_mul_f32 v[4:5], v[72:73], v[4:5] op_sel_hi:[0,1]
	v_pk_fma_f32 v[4:5], v[8:9], v[66:67], v[4:5] op_sel_hi:[1,0,1]
	v_cvt_pk_bf16_f32 v142, v2, v3
	v_pk_add_f32 v[6:7], v[6:7], 1.0 op_sel_hi:[1,0]
	v_pk_mul_f32 v[4:5], v[0:1], v[4:5] op_sel_hi:[0,1]
	v_rcp_f32_e32 v9, v7
	s_nop 0
	v_mul_f32_e32 v7, v19, v9
	v_rcp_f32_e32 v9, v6
	s_nop 0
	v_mul_f32_e32 v6, v18, v9
	v_pk_mul_f32 v[4:5], v[6:7], v[4:5]
	s_waitcnt vmcnt(7)
; DI unsigned pk2(float lo, float hi) { f32x2 v = {lo, hi}; return __builtin_bit_cast(unsigned, __builtin_convertvector(v, bf2_t)); }
; DI float bflo(unsigned w) { return __uint_as_float(w << 16); }
; DI float bfhi(unsigned w) { return __uint_as_float(w & 0xffff0000u); }
; DI void attn_unit(const Params& p, int b, int h, int qb, LAS unsigned char* lds, int tid, int lane, int wave) {
;     ...
; #pragma unroll
;         for (int i = 0; i < 4; ++i)
; #pragma unroll
;             for (int q = 0; q < 4; ++q) {
;                 float gv[4] = {bflo(gw[i][q].x), bfhi(gw[i][q].x), bflo(gw[i][q].y), bfhi(gw[i][q].y)}; float ov[4];
; #pragma unroll
;                 for (int e = 0; e < 4; ++e) { const float val = (o[i][q * 4 + e] * a0 + MB[(i * 16 + q * 4 + e) * 64] * a1) * inv; ov[e] = val * (gv[e] / (1.f + __expf(-gv[e]))); }
;                 *(u32x2*)(op + i * 32 + q * 8) = (u32x2){pk2(ov[0], ov[1]), pk2(ov[2], ov[3])};
;             }
	v_lshlrev_b32_e32 v6, 16, v74
	v_and_b32_e32 v7, 0xffff0000, v74
	v_cvt_pk_bf16_f32 v143, v4, v5
	v_mul_f32_e32 v4, 0xbfb8aa3b, v6
	v_mul_f32_e32 v5, 0xbfb8aa3b, v7
	v_exp_f32_e32 v4, v4
	v_exp_f32_e32 v5, v5
	s_nop 1
	v_permlane32_swap_b32_e32 v140, v142
	v_permlane32_swap_b32_e32 v141, v143
	global_store_dwordx4 v[148:149], v[140:143], off offset:192
	ds_read2st64_b32 v[2:3], v104 offset0:56 offset1:57
	v_pk_add_f32 v[4:5], v[4:5], 1.0 op_sel_hi:[1,0]
	s_nop 0
	v_div_scale_f32 v8, s[0:1], v5, v5, v7
	v_rcp_f32_e32 v9, v8
	s_waitcnt lgkmcnt(0)
	v_pk_mul_f32 v[2:3], v[72:73], v[2:3] op_sel_hi:[0,1]
	v_pk_fma_f32 v[2:3], v[10:11], v[66:67], v[2:3] op_sel_hi:[1,0,1]
	v_fma_f32 v10, -v8, v9, 1.0
	v_fmac_f32_e32 v9, v10, v9
	v_div_scale_f32 v10, vcc, v7, v5, v7
	v_mul_f32_e32 v11, v10, v9
	v_fma_f32 v18, -v8, v11, v10
	v_fmac_f32_e32 v11, v18, v9
	v_fma_f32 v8, -v8, v11, v10
	v_div_fmas_f32 v8, v8, v9, v11
	v_div_fixup_f32 v5, v8, v5, v7
	v_div_scale_f32 v7, s[0:1], v4, v4, v6
	v_rcp_f32_e32 v8, v7
	v_pk_mul_f32 v[2:3], v[0:1], v[2:3] op_sel_hi:[0,1]
	v_fma_f32 v9, -v7, v8, 1.0
	v_fmac_f32_e32 v8, v9, v8
	v_div_scale_f32 v9, vcc, v6, v4, v6
	v_mul_f32_e32 v10, v9, v8
	v_fma_f32 v11, -v7, v10, v9
	v_fmac_f32_e32 v10, v11, v8
	v_fma_f32 v7, -v7, v10, v9
	v_div_fmas_f32 v7, v7, v8, v10
	v_lshlrev_b32_e32 v8, 16, v75
	v_and_b32_e32 v9, 0xffff0000, v75
	v_div_fixup_f32 v4, v7, v4, v6
	v_mul_f32_e32 v6, 0xbfb8aa3b, v8
	v_mul_f32_e32 v7, 0xbfb8aa3b, v9
	v_exp_f32_e32 v6, v6
	v_exp_f32_e32 v7, v7
	v_pk_mul_f32 v[2:3], v[4:5], v[2:3]
	ds_read2st64_b32 v[4:5], v104 offset0:58 offset1:59
	v_cvt_pk_bf16_f32 v144, v2, v3
	v_pk_add_f32 v[6:7], v[6:7], 1.0 op_sel_hi:[1,0]
	s_waitcnt lgkmcnt(0)
	v_pk_mul_f32 v[4:5], v[72:73], v[4:5] op_sel_hi:[0,1]
	v_div_scale_f32 v10, s[0:1], v7, v7, v9
	v_rcp_f32_e32 v11, v10
	v_pk_fma_f32 v[4:5], v[12:13], v[66:67], v[4:5] op_sel_hi:[1,0,1]
	v_fma_f32 v12, -v10, v11, 1.0
	v_fmac_f32_e32 v11, v12, v11
	v_div_scale_f32 v12, vcc, v9, v7, v9
	v_mul_f32_e32 v13, v12, v11
	v_fma_f32 v18, -v10, v13, v12
	v_fmac_f32_e32 v13, v18, v11
	v_fma_f32 v10, -v10, v13, v12
	v_div_fmas_f32 v10, v10, v11, v13
	v_div_fixup_f32 v7, v10, v7, v9
	v_div_scale_f32 v9, s[0:1], v6, v6, v8
	v_rcp_f32_e32 v10, v9
	v_pk_mul_f32 v[4:5], v[0:1], v[4:5] op_sel_hi:[0,1]
	v_fma_f32 v11, -v9, v10, 1.0
	v_fmac_f32_e32 v10, v11, v10
	v_div_scale_f32 v11, vcc, v8, v6, v8
	v_mul_f32_e32 v12, v11, v10
	v_fma_f32 v13, -v9, v12, v11
	v_fmac_f32_e32 v12, v13, v10
	v_fma_f32 v9, -v9, v12, v11
	v_div_fmas_f32 v9, v9, v10, v12
	v_div_fixup_f32 v6, v9, v6, v8
	v_pk_mul_f32 v[4:5], v[6:7], v[4:5]
	s_waitcnt vmcnt(7)
	v_lshlrev_b32_e32 v6, 16, v70
	v_and_b32_e32 v7, 0xffff0000, v70
	v_cvt_pk_bf16_f32 v145, v4, v5
	v_mul_f32_e32 v4, 0xbfb8aa3b, v6
	v_mul_f32_e32 v5, 0xbfb8aa3b, v7
	v_exp_f32_e32 v4, v4
	v_exp_f32_e32 v5, v5
	ds_read2st64_b32 v[2:3], v104 offset0:60 offset1:61
	v_pk_add_f32 v[4:5], v[4:5], 1.0 op_sel_hi:[1,0]
	s_nop 0
	v_div_scale_f32 v8, s[0:1], v5, v5, v7
	v_rcp_f32_e32 v9, v8
	s_waitcnt lgkmcnt(0)
	v_pk_mul_f32 v[2:3], v[72:73], v[2:3] op_sel_hi:[0,1]
	v_pk_fma_f32 v[2:3], v[14:15], v[66:67], v[2:3] op_sel_hi:[1,0,1]
	v_fma_f32 v10, -v8, v9, 1.0
	v_fmac_f32_e32 v9, v10, v9
	v_div_scale_f32 v10, vcc, v7, v5, v7
	v_mul_f32_e32 v11, v10, v9
	v_fma_f32 v12, -v8, v11, v10
	v_fmac_f32_e32 v11, v12, v9
	v_fma_f32 v8, -v8, v11, v10
	v_div_fmas_f32 v8, v8, v9, v11
	v_div_fixup_f32 v5, v8, v5, v7
	v_div_scale_f32 v7, s[0:1], v4, v4, v6
	v_rcp_f32_e32 v8, v7
	v_pk_mul_f32 v[2:3], v[0:1], v[2:3] op_sel_hi:[0,1]
	v_fma_f32 v9, -v7, v8, 1.0
	v_fmac_f32_e32 v8, v9, v8
	v_div_scale_f32 v9, vcc, v6, v4, v6
	v_mul_f32_e32 v10, v9, v8
	v_fma_f32 v11, -v7, v10, v9
	v_fmac_f32_e32 v10, v11, v8
	v_fma_f32 v7, -v7, v10, v9
	v_div_fmas_f32 v7, v7, v8, v10
	v_div_fixup_f32 v4, v7, v4, v6
	v_pk_mul_f32 v[2:3], v[4:5], v[2:3]
	ds_read2st64_b32 v[4:5], v104 offset0:62 offset1:63
	v_lshlrev_b32_e32 v8, 16, v71
	v_and_b32_e32 v9, 0xffff0000, v71
	v_mul_f32_e32 v6, 0xbfb8aa3b, v8
	v_exp_f32_e32 v6, v6
	s_waitcnt lgkmcnt(0)
	v_pk_mul_f32 v[4:5], v[72:73], v[4:5] op_sel_hi:[0,1]
	v_pk_fma_f32 v[4:5], v[16:17], v[66:67], v[4:5] op_sel_hi:[1,0,1]
	v_cvt_pk_bf16_f32 v146, v2, v3
	v_pk_mul_f32 v[4:5], v[0:1], v[4:5] op_sel_hi:[0,1]
	v_mul_f32_e32 v0, 0xbfb8aa3b, v9
	v_exp_f32_e32 v7, v0
	s_nop 0
	v_pk_add_f32 v[6:7], v[6:7], 1.0 op_sel_hi:[1,0]
	s_nop 0
	v_rcp_f32_e32 v10, v7
	s_nop 0
	v_mul_f32_e32 v7, v9, v10
	v_rcp_f32_e32 v9, v6
	s_nop 0
	v_mul_f32_e32 v6, v8, v9
	v_pk_mul_f32 v[4:5], v[6:7], v[4:5]
	s_nop 0
	v_cvt_pk_bf16_f32 v147, v4, v5
	s_nop 1
	v_permlane32_swap_b32_e32 v144, v146
	v_permlane32_swap_b32_e32 v145, v147
	global_store_dwordx4 v[148:149], v[144:147], off offset:224

; DI unsigned pk2(float lo, float hi) { f32x2 v = {lo, hi}; return __builtin_bit_cast(unsigned, __builtin_convertvector(v, bf2_t)); }
; DI float bflo(unsigned w) { return __uint_as_float(w << 16); }
; DI float bfhi(unsigned w) { return __uint_as_float(w & 0xffff0000u); }
; DI void attn_unit(const Params& p, int b, int h, int qb, LAS unsigned char* lds, int tid, int lane, int wave) {
;     ...
;     if (g == 0) {
;         const float m1 = MB[64 * 64], l1 = MB[65 * 64];
;         const float m = fmaxf(mrow, m1);
;         const float a0 = __builtin_amdgcn_exp2f(mrow - m), a1 = __builtin_amdgcn_exp2f(m1 - m);
;         const float inv = 1.0f / (lrow * a0 + l1 * a1);
;         const size_t tok = tokb + qr0 + r;
;         const bf16_t* gp = Z + tok * ZLD + Z_MG + h * 128 + 4 * hh;
;         bf16_t* op = OB + tok * DM + 512 + h * 128 + 4 * hh;
;         u32x2 gw[4][4];
; #pragma unroll
;         for (int i = 0; i < 4; ++i)
; #pragma unroll
;             for (int q = 0; q < 4; ++q) gw[i][q] = *(const u32x2*)(gp + i * 32 + q * 8);
; #pragma unroll
;         for (int i = 0; i < 4; ++i)
; #pragma unroll
;             for (int q = 0; q < 4; ++q) {
;                 float gv[4] = {bflo(gw[i][q].x), bfhi(gw[i][q].x), bflo(gw[i][q].y), bfhi(gw[i][q].y)}; float ov[4];
; #pragma unroll
;                 for (int e = 0; e < 4; ++e) { const float val = (o[i][q * 4 + e] * a0 + MB[(i * 16 + q * 4 + e) * 64] * a1) * inv; ov[e] = val * (gv[e] / (1.f + __expf(-gv[e]))); }
;                 *(u32x2*)(op + i * 32 + q * 8) = (u32x2){pk2(ov[0], ov[1]), pk2(ov[2], ov[3])};
;             }
.LBB0_460:
	s_cmp_gt_u32 s3, 3
	s_waitcnt lgkmcnt(0)
	s_barrier
	s_cbranch_scc1 .LBB0_425
	ds_read2st64_b32 v[70:71], v104 offset0:64 offset1:65
	v_max_f32_e32 v0, v204, v204
	s_lshl_b32 s92, s2, 8
	v_ashrrev_i32_e32 v183, 31, v182
	v_lshlrev_b64 v[102:103], 1, v[182:183]
	s_waitcnt lgkmcnt(0)
	v_max_f32_e32 v66, v70, v70
	v_max_f32_e32 v0, v0, v66
	v_sub_f32_e32 v66, v204, v0
	v_sub_f32_e32 v0, v70, v0
	v_exp_f32_e32 v66, v66
	v_exp_f32_e32 v67, v0
	v_mov_b32_e32 v69, v71
	v_lshlrev_b32_e32 v0, 12, v202
	s_mov_b64 s[0:1], 0x4600c00
	v_pk_mul_f32 v[68:69], v[68:69], v[66:67]
	s_nop 0
	v_add_f32_e32 v105, v68, v69
	v_lshl_add_u64 v[68:69], s[50:51], 0, v[0:1]
	v_lshl_add_u64 v[70:71], v[68:69], 0, s[92:93]
	v_lshlrev_b32_e32 v0, 11, v202
	v_lshl_add_u64 v[70:71], v[70:71], 0, v[102:103]
	v_sub_co_u32_e32 v72, vcc, 0, v0
	v_lshl_add_u64 v[106:107], v[70:71], 0, s[0:1]
	s_nop 0
	v_subb_co_u32_e64 v73, s[0:1], 0, 0, vcc
	s_mov_b32 s0, 0x4600000
	s_nop 0
	v_add_co_u32_e32 v70, vcc, s0, v70
	v_lshl_add_u64 v[68:69], v[68:69], 0, v[72:73]
	s_nop 0
	v_addc_co_u32_e32 v71, vcc, 0, v71, vcc
	global_load_dwordx2 v[72:73], v[70:71], off offset:3072
	global_load_dwordx2 v[100:101], v[106:107], off offset:16
	global_load_dwordx2 v[98:99], v[106:107], off offset:32
	global_load_dwordx2 v[96:97], v[106:107], off offset:48
	global_load_dwordx2 v[94:95], v[106:107], off offset:64
	global_load_dwordx2 v[92:93], v[106:107], off offset:80
	global_load_dwordx2 v[90:91], v[106:107], off offset:96
	global_load_dwordx2 v[88:89], v[106:107], off offset:112
	global_load_dwordx2 v[86:87], v[106:107], off offset:128
	global_load_dwordx2 v[84:85], v[106:107], off offset:144
	global_load_dwordx2 v[82:83], v[106:107], off offset:160
	global_load_dwordx2 v[80:81], v[106:107], off offset:176
	global_load_dwordx2 v[78:79], v[106:107], off offset:192
	global_load_dwordx2 v[76:77], v[106:107], off offset:208
	global_load_dwordx2 v[74:75], v[106:107], off offset:224
	global_load_dwordx2 v[70:71], v[106:107], off offset:240
	v_div_scale_f32 v0, s[0:1], v105, v105, 1.0
	v_rcp_f32_e32 v106, v0
	v_lshl_add_u64 v[68:69], v[68:69], 0, s[92:93]
	v_lshl_add_u64 v[102:103], v[68:69], 0, v[102:103]
	s_mov_b64 s[0:1], 0xae00400
	v_fma_f32 v107, -v0, v106, 1.0
	v_fmac_f32_e32 v106, v107, v106
	v_div_scale_f32 v107, vcc, 1.0, v105, 1.0
	v_mul_f32_e32 v108, v107, v106
	v_fma_f32 v109, -v0, v108, v107
	v_fmac_f32_e32 v108, v109, v106
	v_fma_f32 v0, -v0, v108, v107
	v_div_fmas_f32 v0, v0, v106, v108
	ds_read2st64_b32 v[106:107], v104 offset1:1
	v_div_fixup_f32 v0, v0, v105, 1.0
	v_lshl_add_u64 v[68:69], v[102:103], 0, s[0:1]
	s_waitcnt vmcnt(15)
	v_lshlrev_b32_e32 v105, 16, v72
	v_and_b32_e32 v110, 0xffff0000, v72
	v_mul_f32_e32 v72, 0xbfb8aa3b, v105
	v_exp_f32_e32 v108, v72
	v_mov_b32_e32 v72, v67
	s_waitcnt lgkmcnt(0)
	v_pk_mul_f32 v[106:107], v[72:73], v[106:107] op_sel_hi:[0,1]
	v_pk_fma_f32 v[50:51], v[50:51], v[66:67], v[106:107] op_sel_hi:[1,0,1]
	v_mul_f32_e32 v67, 0xbfb8aa3b, v110
	v_exp_f32_e32 v109, v67
	v_pk_mul_f32 v[50:51], v[0:1], v[50:51] op_sel_hi:[0,1]
	v_pk_add_f32 v[106:107], v[108:109], 1.0 op_sel_hi:[1,0]
	s_nop 0
	v_rcp_f32_e32 v108, v107
	s_nop 0
	v_mul_f32_e32 v107, v110, v108
	v_rcp_f32_e32 v108, v106
	s_nop 0
	v_mul_f32_e32 v106, v105, v108
	v_lshlrev_b32_e32 v67, 16, v73
	v_pk_mul_f32 v[50:51], v[106:107], v[50:51]
	ds_read2st64_b32 v[106:107], v104 offset0:2 offset1:3
	v_and_b32_e32 v73, 0xffff0000, v73
	v_mul_f32_e32 v105, 0xbfb8aa3b, v67
	v_exp_f32_e32 v108, v105
	v_mul_f32_e32 v105, 0xbfb8aa3b, v73
	v_exp_f32_e32 v109, v105
	s_waitcnt lgkmcnt(0)
	v_pk_mul_f32 v[106:107], v[72:73], v[106:107] op_sel_hi:[0,1]
	v_pk_fma_f32 v[52:53], v[52:53], v[66:67], v[106:107] op_sel_hi:[1,0,1]
	v_cvt_pk_bf16_f32 v116, v50, v51
	v_pk_add_f32 v[106:107], v[108:109], 1.0 op_sel_hi:[1,0]
	v_pk_mul_f32 v[52:53], v[0:1], v[52:53] op_sel_hi:[0,1]
	v_rcp_f32_e32 v108, v107
	s_nop 0
	v_mul_f32_e32 v107, v73, v108
	v_div_scale_f32 v73, s[0:1], v106, v106, v67
	v_rcp_f32_e32 v105, v73
	s_mov_b32 s0, 0xae00000
	v_fma_f32 v108, -v73, v105, 1.0
	v_fmac_f32_e32 v105, v108, v105
	v_div_scale_f32 v108, vcc, v67, v106, v67
	v_mul_f32_e32 v109, v108, v105
	v_fma_f32 v110, -v73, v109, v108
	v_fmac_f32_e32 v109, v110, v105
	v_fma_f32 v73, -v73, v109, v108
	v_div_fmas_f32 v73, v73, v105, v109
	v_div_fixup_f32 v106, v73, v106, v67
	v_pk_mul_f32 v[52:53], v[106:107], v[52:53]
	s_waitcnt vmcnt(14)
	v_lshlrev_b32_e32 v67, 16, v100
	v_cvt_pk_bf16_f32 v117, v52, v53
	v_add_co_u32_e32 v52, vcc, s0, v102
	v_and_b32_e32 v73, 0xffff0000, v100
	s_nop 0
	v_addc_co_u32_e32 v53, vcc, 0, v103, vcc
	ds_read2st64_b32 v[50:51], v104 offset0:4 offset1:5
	v_mul_f32_e32 v52, 0xbfb8aa3b, v67
	v_mul_f32_e32 v53, 0xbfb8aa3b, v73
	v_exp_f32_e32 v52, v52
	v_exp_f32_e32 v53, v53
	s_waitcnt lgkmcnt(0)
	v_pk_mul_f32 v[50:51], v[72:73], v[50:51] op_sel_hi:[0,1]
	v_pk_fma_f32 v[50:51], v[54:55], v[66:67], v[50:51] op_sel_hi:[1,0,1]
	v_pk_add_f32 v[52:53], v[52:53], 1.0 op_sel_hi:[1,0]
	s_nop 0
	v_div_scale_f32 v54, s[0:1], v53, v53, v73
	v_rcp_f32_e32 v55, v54
	v_pk_mul_f32 v[50:51], v[0:1], v[50:51] op_sel_hi:[0,1]
	v_fma_f32 v100, -v54, v55, 1.0
	v_fmac_f32_e32 v55, v100, v55
	v_div_scale_f32 v100, vcc, v73, v53, v73
	v_mul_f32_e32 v102, v100, v55
	v_fma_f32 v103, -v54, v102, v100
	v_fmac_f32_e32 v102, v103, v55
	v_fma_f32 v54, -v54, v102, v100
	v_div_fmas_f32 v54, v54, v55, v102
	v_div_fixup_f32 v53, v54, v53, v73
	v_rcp_f32_e32 v55, v52
	s_nop 0
	v_mul_f32_e32 v52, v67, v55
	v_lshlrev_b32_e32 v67, 16, v101
	v_and_b32_e32 v73, 0xffff0000, v101
	v_pk_mul_f32 v[50:51], v[52:53], v[50:51]
	ds_read2st64_b32 v[52:53], v104 offset0:6 offset1:7
	v_mul_f32_e32 v54, 0xbfb8aa3b, v67
	v_mul_f32_e32 v55, 0xbfb8aa3b, v73
	v_exp_f32_e32 v54, v54
	v_exp_f32_e32 v55, v55
	s_waitcnt lgkmcnt(0)
; DI unsigned pk2(float lo, float hi) { f32x2 v = {lo, hi}; return __builtin_bit_cast(unsigned, __builtin_convertvector(v, bf2_t)); }
; DI float bflo(unsigned w) { return __uint_as_float(w << 16); }
; DI float bfhi(unsigned w) { return __uint_as_float(w & 0xffff0000u); }
; DI void attn_unit(const Params& p, int b, int h, int qb, LAS unsigned char* lds, int tid, int lane, int wave) {
;     ...
; #pragma unroll
;         for (int i = 0; i < 4; ++i)
; #pragma unroll
;             for (int q = 0; q < 4; ++q) {
;                 float gv[4] = {bflo(gw[i][q].x), bfhi(gw[i][q].x), bflo(gw[i][q].y), bfhi(gw[i][q].y)}; float ov[4];
; #pragma unroll
;                 for (int e = 0; e < 4; ++e) { const float val = (o[i][q * 4 + e] * a0 + MB[(i * 16 + q * 4 + e) * 64] * a1) * inv; ov[e] = val * (gv[e] / (1.f + __expf(-gv[e]))); }
;                 *(u32x2*)(op + i * 32 + q * 8) = (u32x2){pk2(ov[0], ov[1]), pk2(ov[2], ov[3])};
;             }
	v_pk_mul_f32 v[52:53], v[72:73], v[52:53] op_sel_hi:[0,1]
	v_pk_fma_f32 v[52:53], v[56:57], v[66:67], v[52:53] op_sel_hi:[1,0,1]
	v_cvt_pk_bf16_f32 v118, v50, v51
	v_pk_add_f32 v[54:55], v[54:55], 1.0 op_sel_hi:[1,0]
	v_pk_mul_f32 v[52:53], v[0:1], v[52:53] op_sel_hi:[0,1]
	v_rcp_f32_e32 v57, v55
	s_nop 0
	v_mul_f32_e32 v55, v73, v57
	v_rcp_f32_e32 v57, v54
	s_nop 0
	v_mul_f32_e32 v54, v67, v57
	v_pk_mul_f32 v[52:53], v[54:55], v[52:53]
	s_waitcnt vmcnt(13)
	v_lshlrev_b32_e32 v54, 16, v98
	v_and_b32_e32 v55, 0xffff0000, v98
	v_cvt_pk_bf16_f32 v119, v52, v53
	v_mul_f32_e32 v52, 0xbfb8aa3b, v54
	v_mul_f32_e32 v53, 0xbfb8aa3b, v55
	v_exp_f32_e32 v52, v52
	v_exp_f32_e32 v53, v53
	v_lshlrev_b32_e32 v150, 1, v182
	v_mov_b32_e32 v151, 0
	v_lshl_add_u64 v[148:149], v[150:151], 0, v[68:69]
	s_nop 1
	v_permlane32_swap_b32_e32 v116, v118
	v_permlane32_swap_b32_e32 v117, v119
	global_store_dwordx4 v[148:149], v[116:119], off
	ds_read2st64_b32 v[50:51], v104 offset0:8 offset1:9
	v_pk_add_f32 v[52:53], v[52:53], 1.0 op_sel_hi:[1,0]
	s_nop 0
	v_div_scale_f32 v56, s[0:1], v53, v53, v55
	v_rcp_f32_e32 v57, v56
	s_waitcnt lgkmcnt(0)
	v_pk_mul_f32 v[50:51], v[72:73], v[50:51] op_sel_hi:[0,1]
	v_pk_fma_f32 v[50:51], v[58:59], v[66:67], v[50:51] op_sel_hi:[1,0,1]
	v_fma_f32 v58, -v56, v57, 1.0
	v_fmac_f32_e32 v57, v58, v57
	v_div_scale_f32 v58, vcc, v55, v53, v55
	v_mul_f32_e32 v59, v58, v57
	v_fma_f32 v67, -v56, v59, v58
	v_fmac_f32_e32 v59, v67, v57
	v_fma_f32 v56, -v56, v59, v58
	v_div_fmas_f32 v56, v56, v57, v59
	v_div_fixup_f32 v53, v56, v53, v55
	v_div_scale_f32 v55, s[0:1], v52, v52, v54
	v_rcp_f32_e32 v56, v55
	v_pk_mul_f32 v[50:51], v[0:1], v[50:51] op_sel_hi:[0,1]
	v_fma_f32 v57, -v55, v56, 1.0
	v_fmac_f32_e32 v56, v57, v56
	v_div_scale_f32 v57, vcc, v54, v52, v54
	v_mul_f32_e32 v58, v57, v56
	v_fma_f32 v59, -v55, v58, v57
	v_fmac_f32_e32 v58, v59, v56
	v_fma_f32 v55, -v55, v58, v57
	v_div_fmas_f32 v55, v55, v56, v58
	v_lshlrev_b32_e32 v56, 16, v99
	v_and_b32_e32 v57, 0xffff0000, v99
	v_div_fixup_f32 v52, v55, v52, v54
	v_mul_f32_e32 v54, 0xbfb8aa3b, v56
	v_mul_f32_e32 v55, 0xbfb8aa3b, v57
	v_exp_f32_e32 v54, v54
	v_exp_f32_e32 v55, v55
	v_pk_mul_f32 v[50:51], v[52:53], v[50:51]
	ds_read2st64_b32 v[52:53], v104 offset0:10 offset1:11
	v_cvt_pk_bf16_f32 v120, v50, v51
	v_pk_add_f32 v[54:55], v[54:55], 1.0 op_sel_hi:[1,0]
	s_waitcnt lgkmcnt(0)
	v_pk_mul_f32 v[52:53], v[72:73], v[52:53] op_sel_hi:[0,1]
	v_div_scale_f32 v58, s[0:1], v55, v55, v57
	v_rcp_f32_e32 v59, v58
	v_pk_fma_f32 v[52:53], v[60:61], v[66:67], v[52:53] op_sel_hi:[1,0,1]
	v_fma_f32 v60, -v58, v59, 1.0
	v_fmac_f32_e32 v59, v60, v59
	v_div_scale_f32 v60, vcc, v57, v55, v57
	v_mul_f32_e32 v61, v60, v59
	v_fma_f32 v67, -v58, v61, v60
	v_fmac_f32_e32 v61, v67, v59
	v_fma_f32 v58, -v58, v61, v60
	v_div_fmas_f32 v58, v58, v59, v61
	v_div_fixup_f32 v55, v58, v55, v57
	v_div_scale_f32 v57, s[0:1], v54, v54, v56
	v_rcp_f32_e32 v58, v57
	v_pk_mul_f32 v[52:53], v[0:1], v[52:53] op_sel_hi:[0,1]
	v_fma_f32 v59, -v57, v58, 1.0
	v_fmac_f32_e32 v58, v59, v58
	v_div_scale_f32 v59, vcc, v56, v54, v56
	v_mul_f32_e32 v60, v59, v58
	v_fma_f32 v61, -v57, v60, v59
	v_fmac_f32_e32 v60, v61, v58
	v_fma_f32 v57, -v57, v60, v59
	v_div_fmas_f32 v57, v57, v58, v60
	v_div_fixup_f32 v54, v57, v54, v56
	v_pk_mul_f32 v[52:53], v[54:55], v[52:53]
	s_waitcnt vmcnt(13)
	v_lshlrev_b32_e32 v54, 16, v96
	v_and_b32_e32 v55, 0xffff0000, v96
	v_cvt_pk_bf16_f32 v121, v52, v53
	v_mul_f32_e32 v52, 0xbfb8aa3b, v54
	v_mul_f32_e32 v53, 0xbfb8aa3b, v55
	v_exp_f32_e32 v52, v52
	v_exp_f32_e32 v53, v53
	ds_read2st64_b32 v[50:51], v104 offset0:12 offset1:13
	v_pk_add_f32 v[52:53], v[52:53], 1.0 op_sel_hi:[1,0]
	s_nop 0
	v_div_scale_f32 v56, s[0:1], v53, v53, v55
	v_rcp_f32_e32 v57, v56
	s_waitcnt lgkmcnt(0)
	v_pk_mul_f32 v[50:51], v[72:73], v[50:51] op_sel_hi:[0,1]
	v_pk_fma_f32 v[50:51], v[62:63], v[66:67], v[50:51] op_sel_hi:[1,0,1]
	v_fma_f32 v58, -v56, v57, 1.0
	v_fmac_f32_e32 v57, v58, v57
	v_div_scale_f32 v58, vcc, v55, v53, v55
	v_mul_f32_e32 v59, v58, v57
	v_fma_f32 v60, -v56, v59, v58
	v_fmac_f32_e32 v59, v60, v57
	v_fma_f32 v56, -v56, v59, v58
	v_div_fmas_f32 v56, v56, v57, v59
	v_div_fixup_f32 v53, v56, v53, v55
	v_div_scale_f32 v55, s[0:1], v52, v52, v54
	v_rcp_f32_e32 v56, v55
	v_pk_mul_f32 v[50:51], v[0:1], v[50:51] op_sel_hi:[0,1]
	v_fma_f32 v57, -v55, v56, 1.0
	v_fmac_f32_e32 v56, v57, v56
	v_div_scale_f32 v57, vcc, v54, v52, v54
	v_mul_f32_e32 v58, v57, v56
	v_fma_f32 v59, -v55, v58, v57
	v_fmac_f32_e32 v58, v59, v56
	v_fma_f32 v55, -v55, v58, v57
	v_div_fmas_f32 v55, v55, v56, v58
	v_lshlrev_b32_e32 v56, 16, v97
	v_and_b32_e32 v57, 0xffff0000, v97
	v_div_fixup_f32 v52, v55, v52, v54
	v_mul_f32_e32 v54, 0xbfb8aa3b, v56
	v_mul_f32_e32 v55, 0xbfb8aa3b, v57
	v_exp_f32_e32 v54, v54
	v_exp_f32_e32 v55, v55
	v_pk_mul_f32 v[50:51], v[52:53], v[50:51]
	ds_read2st64_b32 v[52:53], v104 offset0:14 offset1:15
	v_cvt_pk_bf16_f32 v122, v50, v51
	v_pk_add_f32 v[54:55], v[54:55], 1.0 op_sel_hi:[1,0]
	s_waitcnt lgkmcnt(0)
	v_pk_mul_f32 v[52:53], v[72:73], v[52:53] op_sel_hi:[0,1]
	v_div_scale_f32 v58, s[0:1], v55, v55, v57
	v_rcp_f32_e32 v59, v58
	v_pk_fma_f32 v[52:53], v[64:65], v[66:67], v[52:53] op_sel_hi:[1,0,1]
	v_fma_f32 v60, -v58, v59, 1.0
	v_fmac_f32_e32 v59, v60, v59
	v_div_scale_f32 v60, vcc, v57, v55, v57
	v_mul_f32_e32 v61, v60, v59
	v_fma_f32 v62, -v58, v61, v60
	v_fmac_f32_e32 v61, v62, v59
	v_fma_f32 v58, -v58, v61, v60
	v_div_fmas_f32 v58, v58, v59, v61
	v_div_fixup_f32 v55, v58, v55, v57
	v_div_scale_f32 v57, s[0:1], v54, v54, v56
	v_rcp_f32_e32 v58, v57
	v_pk_mul_f32 v[52:53], v[0:1], v[52:53] op_sel_hi:[0,1]
	v_fma_f32 v59, -v57, v58, 1.0
	v_fmac_f32_e32 v58, v59, v58
	v_div_scale_f32 v59, vcc, v56, v54, v56
	v_mul_f32_e32 v60, v59, v58
	v_fma_f32 v61, -v57, v60, v59
	v_fmac_f32_e32 v60, v61, v58
	v_fma_f32 v57, -v57, v60, v59
	v_div_fmas_f32 v57, v57, v58, v60
	v_div_fixup_f32 v54, v57, v54, v56
	v_pk_mul_f32 v[52:53], v[54:55], v[52:53]
	s_waitcnt vmcnt(12)
; DI unsigned pk2(float lo, float hi) { f32x2 v = {lo, hi}; return __builtin_bit_cast(unsigned, __builtin_convertvector(v, bf2_t)); }
; DI float bflo(unsigned w) { return __uint_as_float(w << 16); }
; DI float bfhi(unsigned w) { return __uint_as_float(w & 0xffff0000u); }
; DI void attn_unit(const Params& p, int b, int h, int qb, LAS unsigned char* lds, int tid, int lane, int wave) {
;     ...
; #pragma unroll
;         for (int i = 0; i < 4; ++i)
; #pragma unroll
;             for (int q = 0; q < 4; ++q) {
;                 float gv[4] = {bflo(gw[i][q].x), bfhi(gw[i][q].x), bflo(gw[i][q].y), bfhi(gw[i][q].y)}; float ov[4];
; #pragma unroll
;                 for (int e = 0; e < 4; ++e) { const float val = (o[i][q * 4 + e] * a0 + MB[(i * 16 + q * 4 + e) * 64] * a1) * inv; ov[e] = val * (gv[e] / (1.f + __expf(-gv[e]))); }
;                 *(u32x2*)(op + i * 32 + q * 8) = (u32x2){pk2(ov[0], ov[1]), pk2(ov[2], ov[3])};
;             }
	v_lshlrev_b32_e32 v54, 16, v94
	v_cvt_pk_bf16_f32 v123, v52, v53
	s_nop 1
	v_permlane32_swap_b32_e32 v120, v122
	v_permlane32_swap_b32_e32 v121, v123
	global_store_dwordx4 v[148:149], v[120:123], off offset:32
	ds_read2st64_b32 v[50:51], v104 offset0:16 offset1:17
	v_and_b32_e32 v55, 0xffff0000, v94
	v_mul_f32_e32 v52, 0xbfb8aa3b, v54
	v_exp_f32_e32 v52, v52
	s_waitcnt lgkmcnt(0)
	v_pk_mul_f32 v[50:51], v[72:73], v[50:51] op_sel_hi:[0,1]
	v_pk_fma_f32 v[34:35], v[34:35], v[66:67], v[50:51] op_sel_hi:[1,0,1]
	v_mul_f32_e32 v50, 0xbfb8aa3b, v55
	v_exp_f32_e32 v53, v50
	v_pk_mul_f32 v[34:35], v[0:1], v[34:35] op_sel_hi:[0,1]
	v_pk_add_f32 v[50:51], v[52:53], 1.0 op_sel_hi:[1,0]
	s_nop 0
	v_rcp_f32_e32 v53, v51
	s_nop 0
	v_mul_f32_e32 v51, v55, v53
	v_rcp_f32_e32 v53, v50
	s_nop 0
	v_mul_f32_e32 v50, v54, v53
	v_pk_mul_f32 v[34:35], v[50:51], v[34:35]
	ds_read2st64_b32 v[50:51], v104 offset0:18 offset1:19
	v_lshlrev_b32_e32 v54, 16, v95
	v_and_b32_e32 v55, 0xffff0000, v95
	v_mul_f32_e32 v52, 0xbfb8aa3b, v54
	v_exp_f32_e32 v52, v52
	s_waitcnt lgkmcnt(0)
	v_pk_mul_f32 v[50:51], v[72:73], v[50:51] op_sel_hi:[0,1]
	v_pk_fma_f32 v[36:37], v[36:37], v[66:67], v[50:51] op_sel_hi:[1,0,1]
	v_mul_f32_e32 v50, 0xbfb8aa3b, v55
	v_exp_f32_e32 v53, v50
	v_pk_mul_f32 v[36:37], v[0:1], v[36:37] op_sel_hi:[0,1]
	v_cvt_pk_bf16_f32 v124, v34, v35
	v_pk_add_f32 v[50:51], v[52:53], 1.0 op_sel_hi:[1,0]
	s_nop 0
	v_rcp_f32_e32 v53, v51
	s_nop 0
	v_mul_f32_e32 v51, v55, v53
	v_rcp_f32_e32 v53, v50
	s_nop 0
	v_mul_f32_e32 v50, v54, v53
	v_pk_mul_f32 v[36:37], v[50:51], v[36:37]
	s_waitcnt vmcnt(12)
	v_lshlrev_b32_e32 v50, 16, v92
	v_cvt_pk_bf16_f32 v125, v36, v37
	v_and_b32_e32 v51, 0xffff0000, v92
	ds_read2st64_b32 v[34:35], v104 offset0:20 offset1:21
	v_mul_f32_e32 v36, 0xbfb8aa3b, v50
	v_mul_f32_e32 v37, 0xbfb8aa3b, v51
	v_exp_f32_e32 v36, v36
	v_exp_f32_e32 v37, v37
	s_waitcnt lgkmcnt(0)
	v_pk_mul_f32 v[34:35], v[72:73], v[34:35] op_sel_hi:[0,1]
	v_pk_fma_f32 v[34:35], v[38:39], v[66:67], v[34:35] op_sel_hi:[1,0,1]
	v_pk_add_f32 v[36:37], v[36:37], 1.0 op_sel_hi:[1,0]
	s_nop 0
	v_div_scale_f32 v38, s[0:1], v37, v37, v51
	v_rcp_f32_e32 v39, v38
	v_pk_mul_f32 v[34:35], v[0:1], v[34:35] op_sel_hi:[0,1]
	v_fma_f32 v52, -v38, v39, 1.0
	v_fmac_f32_e32 v39, v52, v39
	v_div_scale_f32 v52, vcc, v51, v37, v51
	v_mul_f32_e32 v53, v52, v39
	v_fma_f32 v54, -v38, v53, v52
	v_fmac_f32_e32 v53, v54, v39
	v_fma_f32 v38, -v38, v53, v52
	v_div_fmas_f32 v38, v38, v39, v53
	v_div_fixup_f32 v37, v38, v37, v51
	v_rcp_f32_e32 v39, v36
	s_nop 0
	v_mul_f32_e32 v36, v50, v39
	v_lshlrev_b32_e32 v50, 16, v93
	v_and_b32_e32 v51, 0xffff0000, v93
	v_pk_mul_f32 v[34:35], v[36:37], v[34:35]
	ds_read2st64_b32 v[36:37], v104 offset0:22 offset1:23
	v_mul_f32_e32 v38, 0xbfb8aa3b, v50
	v_mul_f32_e32 v39, 0xbfb8aa3b, v51
	v_exp_f32_e32 v38, v38
	v_exp_f32_e32 v39, v39
	s_waitcnt lgkmcnt(0)
	v_pk_mul_f32 v[36:37], v[72:73], v[36:37] op_sel_hi:[0,1]
	v_pk_fma_f32 v[36:37], v[40:41], v[66:67], v[36:37] op_sel_hi:[1,0,1]
	v_cvt_pk_bf16_f32 v126, v34, v35
	v_pk_add_f32 v[38:39], v[38:39], 1.0 op_sel_hi:[1,0]
	v_pk_mul_f32 v[36:37], v[0:1], v[36:37] op_sel_hi:[0,1]
	v_rcp_f32_e32 v41, v39
	s_nop 0
	v_mul_f32_e32 v39, v51, v41
	v_rcp_f32_e32 v41, v38
	s_nop 0
	v_mul_f32_e32 v38, v50, v41
	v_pk_mul_f32 v[36:37], v[38:39], v[36:37]
	s_waitcnt vmcnt(11)
	v_lshlrev_b32_e32 v38, 16, v90
	v_and_b32_e32 v39, 0xffff0000, v90
	v_cvt_pk_bf16_f32 v127, v36, v37
	v_mul_f32_e32 v36, 0xbfb8aa3b, v38
	v_mul_f32_e32 v37, 0xbfb8aa3b, v39
	v_exp_f32_e32 v36, v36
	v_exp_f32_e32 v37, v37
	s_nop 1
	v_permlane32_swap_b32_e32 v124, v126
	v_permlane32_swap_b32_e32 v125, v127
	global_store_dwordx4 v[148:149], v[124:127], off offset:64
	ds_read2st64_b32 v[34:35], v104 offset0:24 offset1:25
	v_pk_add_f32 v[36:37], v[36:37], 1.0 op_sel_hi:[1,0]
	s_nop 0
	v_div_scale_f32 v40, s[0:1], v37, v37, v39
	v_rcp_f32_e32 v41, v40
	s_waitcnt lgkmcnt(0)
	v_pk_mul_f32 v[34:35], v[72:73], v[34:35] op_sel_hi:[0,1]
	v_pk_fma_f32 v[34:35], v[42:43], v[66:67], v[34:35] op_sel_hi:[1,0,1]
	v_fma_f32 v42, -v40, v41, 1.0
	v_fmac_f32_e32 v41, v42, v41
	v_div_scale_f32 v42, vcc, v39, v37, v39
	v_mul_f32_e32 v43, v42, v41
	v_fma_f32 v50, -v40, v43, v42
	v_fmac_f32_e32 v43, v50, v41
	v_fma_f32 v40, -v40, v43, v42
	v_div_fmas_f32 v40, v40, v41, v43
	v_div_fixup_f32 v37, v40, v37, v39
	v_div_scale_f32 v39, s[0:1], v36, v36, v38
	v_rcp_f32_e32 v40, v39
	v_pk_mul_f32 v[34:35], v[0:1], v[34:35] op_sel_hi:[0,1]
	v_fma_f32 v41, -v39, v40, 1.0
	v_fmac_f32_e32 v40, v41, v40
	v_div_scale_f32 v41, vcc, v38, v36, v38
	v_mul_f32_e32 v42, v41, v40
	v_fma_f32 v43, -v39, v42, v41
	v_fmac_f32_e32 v42, v43, v40
	v_fma_f32 v39, -v39, v42, v41
	v_div_fmas_f32 v39, v39, v40, v42
	v_lshlrev_b32_e32 v40, 16, v91
	v_and_b32_e32 v41, 0xffff0000, v91
	v_div_fixup_f32 v36, v39, v36, v38
	v_mul_f32_e32 v38, 0xbfb8aa3b, v40
	v_mul_f32_e32 v39, 0xbfb8aa3b, v41
	v_exp_f32_e32 v38, v38
	v_exp_f32_e32 v39, v39
	v_pk_mul_f32 v[34:35], v[36:37], v[34:35]
	ds_read2st64_b32 v[36:37], v104 offset0:26 offset1:27
	v_cvt_pk_bf16_f32 v128, v34, v35
	v_pk_add_f32 v[38:39], v[38:39], 1.0 op_sel_hi:[1,0]
	s_waitcnt lgkmcnt(0)
; DI unsigned pk2(float lo, float hi) { f32x2 v = {lo, hi}; return __builtin_bit_cast(unsigned, __builtin_convertvector(v, bf2_t)); }
; DI float bflo(unsigned w) { return __uint_as_float(w << 16); }
; DI float bfhi(unsigned w) { return __uint_as_float(w & 0xffff0000u); }
; DI void attn_unit(const Params& p, int b, int h, int qb, LAS unsigned char* lds, int tid, int lane, int wave) {
;     ...
; #pragma unroll
;         for (int i = 0; i < 4; ++i)
; #pragma unroll
;             for (int q = 0; q < 4; ++q) {
;                 float gv[4] = {bflo(gw[i][q].x), bfhi(gw[i][q].x), bflo(gw[i][q].y), bfhi(gw[i][q].y)}; float ov[4];
; #pragma unroll
;                 for (int e = 0; e < 4; ++e) { const float val = (o[i][q * 4 + e] * a0 + MB[(i * 16 + q * 4 + e) * 64] * a1) * inv; ov[e] = val * (gv[e] / (1.f + __expf(-gv[e]))); }
;                 *(u32x2*)(op + i * 32 + q * 8) = (u32x2){pk2(ov[0], ov[1]), pk2(ov[2], ov[3])};
;             }
	v_pk_mul_f32 v[36:37], v[72:73], v[36:37] op_sel_hi:[0,1]
	v_div_scale_f32 v42, s[0:1], v39, v39, v41
	v_rcp_f32_e32 v43, v42
	v_pk_fma_f32 v[36:37], v[44:45], v[66:67], v[36:37] op_sel_hi:[1,0,1]
	v_fma_f32 v44, -v42, v43, 1.0
	v_fmac_f32_e32 v43, v44, v43
	v_div_scale_f32 v44, vcc, v41, v39, v41
	v_mul_f32_e32 v45, v44, v43
	v_fma_f32 v50, -v42, v45, v44
	v_fmac_f32_e32 v45, v50, v43
	v_fma_f32 v42, -v42, v45, v44
	v_div_fmas_f32 v42, v42, v43, v45
	v_div_fixup_f32 v39, v42, v39, v41
	v_div_scale_f32 v41, s[0:1], v38, v38, v40
	v_rcp_f32_e32 v42, v41
	v_pk_mul_f32 v[36:37], v[0:1], v[36:37] op_sel_hi:[0,1]
	v_fma_f32 v43, -v41, v42, 1.0
	v_fmac_f32_e32 v42, v43, v42
	v_div_scale_f32 v43, vcc, v40, v38, v40
	v_mul_f32_e32 v44, v43, v42
	v_fma_f32 v45, -v41, v44, v43
	v_fmac_f32_e32 v44, v45, v42
	v_fma_f32 v41, -v41, v44, v43
	v_div_fmas_f32 v41, v41, v42, v44
	v_div_fixup_f32 v38, v41, v38, v40
	v_pk_mul_f32 v[36:37], v[38:39], v[36:37]
	s_waitcnt vmcnt(11)
	v_lshlrev_b32_e32 v38, 16, v88
	v_and_b32_e32 v39, 0xffff0000, v88
	v_cvt_pk_bf16_f32 v129, v36, v37
	v_mul_f32_e32 v36, 0xbfb8aa3b, v38
	v_mul_f32_e32 v37, 0xbfb8aa3b, v39
	v_exp_f32_e32 v36, v36
	v_exp_f32_e32 v37, v37
	ds_read2st64_b32 v[34:35], v104 offset0:28 offset1:29
	v_pk_add_f32 v[36:37], v[36:37], 1.0 op_sel_hi:[1,0]
	s_nop 0
	v_div_scale_f32 v40, s[0:1], v37, v37, v39
	v_rcp_f32_e32 v41, v40
	s_waitcnt lgkmcnt(0)
	v_pk_mul_f32 v[34:35], v[72:73], v[34:35] op_sel_hi:[0,1]
	v_pk_fma_f32 v[34:35], v[46:47], v[66:67], v[34:35] op_sel_hi:[1,0,1]
	v_fma_f32 v42, -v40, v41, 1.0
	v_fmac_f32_e32 v41, v42, v41
	v_div_scale_f32 v42, vcc, v39, v37, v39
	v_mul_f32_e32 v43, v42, v41
	v_fma_f32 v44, -v40, v43, v42
	v_fmac_f32_e32 v43, v44, v41
	v_fma_f32 v40, -v40, v43, v42
	v_div_fmas_f32 v40, v40, v41, v43
	v_div_fixup_f32 v37, v40, v37, v39
	v_div_scale_f32 v39, s[0:1], v36, v36, v38
	v_rcp_f32_e32 v40, v39
	v_pk_mul_f32 v[34:35], v[0:1], v[34:35] op_sel_hi:[0,1]
	v_fma_f32 v41, -v39, v40, 1.0
	v_fmac_f32_e32 v40, v41, v40
	v_div_scale_f32 v41, vcc, v38, v36, v38
	v_mul_f32_e32 v42, v41, v40
	v_fma_f32 v43, -v39, v42, v41
	v_fmac_f32_e32 v42, v43, v40
	v_fma_f32 v39, -v39, v42, v41
	v_div_fmas_f32 v39, v39, v40, v42
	v_lshlrev_b32_e32 v40, 16, v89
	v_and_b32_e32 v41, 0xffff0000, v89
	v_div_fixup_f32 v36, v39, v36, v38
	v_mul_f32_e32 v38, 0xbfb8aa3b, v40
	v_mul_f32_e32 v39, 0xbfb8aa3b, v41
	v_exp_f32_e32 v38, v38
	v_exp_f32_e32 v39, v39
	v_pk_mul_f32 v[34:35], v[36:37], v[34:35]
	ds_read2st64_b32 v[36:37], v104 offset0:30 offset1:31
	v_cvt_pk_bf16_f32 v130, v34, v35
	v_pk_add_f32 v[38:39], v[38:39], 1.0 op_sel_hi:[1,0]
	s_waitcnt lgkmcnt(0)
	v_pk_mul_f32 v[36:37], v[72:73], v[36:37] op_sel_hi:[0,1]
	v_div_scale_f32 v42, s[0:1], v39, v39, v41
	v_rcp_f32_e32 v43, v42
	v_pk_fma_f32 v[36:37], v[48:49], v[66:67], v[36:37] op_sel_hi:[1,0,1]
	v_fma_f32 v44, -v42, v43, 1.0
	v_fmac_f32_e32 v43, v44, v43
	v_div_scale_f32 v44, vcc, v41, v39, v41
	v_mul_f32_e32 v45, v44, v43
	v_fma_f32 v46, -v42, v45, v44
	v_fmac_f32_e32 v45, v46, v43
	v_fma_f32 v42, -v42, v45, v44
	v_div_fmas_f32 v42, v42, v43, v45
	v_div_fixup_f32 v39, v42, v39, v41
	v_div_scale_f32 v41, s[0:1], v38, v38, v40
	v_rcp_f32_e32 v42, v41
	v_pk_mul_f32 v[36:37], v[0:1], v[36:37] op_sel_hi:[0,1]
	v_fma_f32 v43, -v41, v42, 1.0
	v_fmac_f32_e32 v42, v43, v42
	v_div_scale_f32 v43, vcc, v40, v38, v40
	v_mul_f32_e32 v44, v43, v42
	v_fma_f32 v45, -v41, v44, v43
	v_fmac_f32_e32 v44, v45, v42
	v_fma_f32 v41, -v41, v44, v43
	v_div_fmas_f32 v41, v41, v42, v44
	v_div_fixup_f32 v38, v41, v38, v40
	v_pk_mul_f32 v[36:37], v[38:39], v[36:37]
	s_waitcnt vmcnt(10)
	v_lshlrev_b32_e32 v38, 16, v86
	v_cvt_pk_bf16_f32 v131, v36, v37
	s_nop 1
	v_permlane32_swap_b32_e32 v128, v130
	v_permlane32_swap_b32_e32 v129, v131
	global_store_dwordx4 v[148:149], v[128:131], off offset:96
	ds_read2st64_b32 v[34:35], v104 offset0:32 offset1:33
	v_and_b32_e32 v39, 0xffff0000, v86
	v_mul_f32_e32 v36, 0xbfb8aa3b, v38
	v_exp_f32_e32 v36, v36
	s_waitcnt lgkmcnt(0)
	v_pk_mul_f32 v[34:35], v[72:73], v[34:35] op_sel_hi:[0,1]
	v_pk_fma_f32 v[18:19], v[18:19], v[66:67], v[34:35] op_sel_hi:[1,0,1]
	v_mul_f32_e32 v34, 0xbfb8aa3b, v39
	v_exp_f32_e32 v37, v34
	v_pk_mul_f32 v[18:19], v[0:1], v[18:19] op_sel_hi:[0,1]
	v_pk_add_f32 v[34:35], v[36:37], 1.0 op_sel_hi:[1,0]
	s_nop 0
	v_rcp_f32_e32 v37, v35
	s_nop 0
	v_mul_f32_e32 v35, v39, v37
	v_rcp_f32_e32 v37, v34
	s_nop 0
	v_mul_f32_e32 v34, v38, v37
	v_pk_mul_f32 v[18:19], v[34:35], v[18:19]
	ds_read2st64_b32 v[34:35], v104 offset0:34 offset1:35
	v_lshlrev_b32_e32 v38, 16, v87
	v_and_b32_e32 v39, 0xffff0000, v87
	v_mul_f32_e32 v36, 0xbfb8aa3b, v38
	v_exp_f32_e32 v36, v36
	s_waitcnt lgkmcnt(0)
	v_pk_mul_f32 v[34:35], v[72:73], v[34:35] op_sel_hi:[0,1]
	v_pk_fma_f32 v[20:21], v[20:21], v[66:67], v[34:35] op_sel_hi:[1,0,1]
	v_mul_f32_e32 v34, 0xbfb8aa3b, v39
	v_exp_f32_e32 v37, v34
	v_pk_mul_f32 v[20:21], v[0:1], v[20:21] op_sel_hi:[0,1]
	v_cvt_pk_bf16_f32 v132, v18, v19
	v_pk_add_f32 v[34:35], v[36:37], 1.0 op_sel_hi:[1,0]
	s_nop 0
	v_rcp_f32_e32 v37, v35
	s_nop 0
	v_mul_f32_e32 v35, v39, v37
	v_rcp_f32_e32 v37, v34
	s_nop 0
	v_mul_f32_e32 v34, v38, v37
	v_pk_mul_f32 v[20:21], v[34:35], v[20:21]
	s_waitcnt vmcnt(10)
	v_lshlrev_b32_e32 v34, 16, v84
	v_cvt_pk_bf16_f32 v133, v20, v21
	v_and_b32_e32 v35, 0xffff0000, v84
	ds_read2st64_b32 v[18:19], v104 offset0:36 offset1:37
	v_mul_f32_e32 v20, 0xbfb8aa3b, v34
	v_mul_f32_e32 v21, 0xbfb8aa3b, v35
	v_exp_f32_e32 v20, v20
	v_exp_f32_e32 v21, v21
	s_waitcnt lgkmcnt(0)
; DI unsigned pk2(float lo, float hi) { f32x2 v = {lo, hi}; return __builtin_bit_cast(unsigned, __builtin_convertvector(v, bf2_t)); }
; DI float bflo(unsigned w) { return __uint_as_float(w << 16); }
; DI float bfhi(unsigned w) { return __uint_as_float(w & 0xffff0000u); }
; DI void attn_unit(const Params& p, int b, int h, int qb, LAS unsigned char* lds, int tid, int lane, int wave) {
;     ...
; #pragma unroll
;         for (int i = 0; i < 4; ++i)
; #pragma unroll
;             for (int q = 0; q < 4; ++q) {
;                 float gv[4] = {bflo(gw[i][q].x), bfhi(gw[i][q].x), bflo(gw[i][q].y), bfhi(gw[i][q].y)}; float ov[4];
; #pragma unroll
;                 for (int e = 0; e < 4; ++e) { const float val = (o[i][q * 4 + e] * a0 + MB[(i * 16 + q * 4 + e) * 64] * a1) * inv; ov[e] = val * (gv[e] / (1.f + __expf(-gv[e]))); }
;                 *(u32x2*)(op + i * 32 + q * 8) = (u32x2){pk2(ov[0], ov[1]), pk2(ov[2], ov[3])};
;             }
	v_pk_mul_f32 v[18:19], v[72:73], v[18:19] op_sel_hi:[0,1]
	v_pk_fma_f32 v[18:19], v[22:23], v[66:67], v[18:19] op_sel_hi:[1,0,1]
	v_pk_add_f32 v[20:21], v[20:21], 1.0 op_sel_hi:[1,0]
	s_nop 0
	v_div_scale_f32 v22, s[0:1], v21, v21, v35
	v_rcp_f32_e32 v23, v22
	v_pk_mul_f32 v[18:19], v[0:1], v[18:19] op_sel_hi:[0,1]
	v_fma_f32 v36, -v22, v23, 1.0
	v_fmac_f32_e32 v23, v36, v23
	v_div_scale_f32 v36, vcc, v35, v21, v35
	v_mul_f32_e32 v37, v36, v23
	v_fma_f32 v38, -v22, v37, v36
	v_fmac_f32_e32 v37, v38, v23
	v_fma_f32 v22, -v22, v37, v36
	v_div_fmas_f32 v22, v22, v23, v37
	v_div_fixup_f32 v21, v22, v21, v35
	v_rcp_f32_e32 v23, v20
	s_nop 0
	v_mul_f32_e32 v20, v34, v23
	v_lshlrev_b32_e32 v34, 16, v85
	v_and_b32_e32 v35, 0xffff0000, v85
	v_pk_mul_f32 v[18:19], v[20:21], v[18:19]
	ds_read2st64_b32 v[20:21], v104 offset0:38 offset1:39
	v_mul_f32_e32 v22, 0xbfb8aa3b, v34
	v_mul_f32_e32 v23, 0xbfb8aa3b, v35
	v_exp_f32_e32 v22, v22
	v_exp_f32_e32 v23, v23
	s_waitcnt lgkmcnt(0)
	v_pk_mul_f32 v[20:21], v[72:73], v[20:21] op_sel_hi:[0,1]
	v_pk_fma_f32 v[20:21], v[24:25], v[66:67], v[20:21] op_sel_hi:[1,0,1]
	v_cvt_pk_bf16_f32 v134, v18, v19
	v_pk_add_f32 v[22:23], v[22:23], 1.0 op_sel_hi:[1,0]
	v_pk_mul_f32 v[20:21], v[0:1], v[20:21] op_sel_hi:[0,1]
	v_rcp_f32_e32 v25, v23
	s_nop 0
	v_mul_f32_e32 v23, v35, v25
	v_rcp_f32_e32 v25, v22
	s_nop 0
	v_mul_f32_e32 v22, v34, v25
	v_pk_mul_f32 v[20:21], v[22:23], v[20:21]
	s_waitcnt vmcnt(9)
	v_lshlrev_b32_e32 v22, 16, v82
	v_and_b32_e32 v23, 0xffff0000, v82
	v_cvt_pk_bf16_f32 v135, v20, v21
	v_mul_f32_e32 v20, 0xbfb8aa3b, v22
	v_mul_f32_e32 v21, 0xbfb8aa3b, v23
	v_exp_f32_e32 v20, v20
	v_exp_f32_e32 v21, v21
	s_nop 1
	v_permlane32_swap_b32_e32 v132, v134
	v_permlane32_swap_b32_e32 v133, v135
	global_store_dwordx4 v[148:149], v[132:135], off offset:128
	ds_read2st64_b32 v[18:19], v104 offset0:40 offset1:41
	v_pk_add_f32 v[20:21], v[20:21], 1.0 op_sel_hi:[1,0]
	s_nop 0
	v_div_scale_f32 v24, s[0:1], v21, v21, v23
	v_rcp_f32_e32 v25, v24
	s_waitcnt lgkmcnt(0)
	v_pk_mul_f32 v[18:19], v[72:73], v[18:19] op_sel_hi:[0,1]
	v_pk_fma_f32 v[18:19], v[26:27], v[66:67], v[18:19] op_sel_hi:[1,0,1]
	v_fma_f32 v26, -v24, v25, 1.0
	v_fmac_f32_e32 v25, v26, v25
	v_div_scale_f32 v26, vcc, v23, v21, v23
	v_mul_f32_e32 v27, v26, v25
	v_fma_f32 v34, -v24, v27, v26
	v_fmac_f32_e32 v27, v34, v25
	v_fma_f32 v24, -v24, v27, v26
	v_div_fmas_f32 v24, v24, v25, v27
	v_div_fixup_f32 v21, v24, v21, v23
	v_div_scale_f32 v23, s[0:1], v20, v20, v22
	v_rcp_f32_e32 v24, v23
	v_pk_mul_f32 v[18:19], v[0:1], v[18:19] op_sel_hi:[0,1]
	v_fma_f32 v25, -v23, v24, 1.0
	v_fmac_f32_e32 v24, v25, v24
	v_div_scale_f32 v25, vcc, v22, v20, v22
	v_mul_f32_e32 v26, v25, v24
	v_fma_f32 v27, -v23, v26, v25
	v_fmac_f32_e32 v26, v27, v24
	v_fma_f32 v23, -v23, v26, v25
	v_div_fmas_f32 v23, v23, v24, v26
	v_lshlrev_b32_e32 v24, 16, v83
	v_and_b32_e32 v25, 0xffff0000, v83
	v_div_fixup_f32 v20, v23, v20, v22
	v_mul_f32_e32 v22, 0xbfb8aa3b, v24
	v_mul_f32_e32 v23, 0xbfb8aa3b, v25
	v_exp_f32_e32 v22, v22
	v_exp_f32_e32 v23, v23
	v_pk_mul_f32 v[18:19], v[20:21], v[18:19]
	ds_read2st64_b32 v[20:21], v104 offset0:42 offset1:43
	v_cvt_pk_bf16_f32 v136, v18, v19
	v_pk_add_f32 v[22:23], v[22:23], 1.0 op_sel_hi:[1,0]
	s_waitcnt lgkmcnt(0)
	v_pk_mul_f32 v[20:21], v[72:73], v[20:21] op_sel_hi:[0,1]
	v_div_scale_f32 v26, s[0:1], v23, v23, v25
	v_rcp_f32_e32 v27, v26
	v_pk_fma_f32 v[20:21], v[28:29], v[66:67], v[20:21] op_sel_hi:[1,0,1]
	v_fma_f32 v28, -v26, v27, 1.0
	v_fmac_f32_e32 v27, v28, v27
	v_div_scale_f32 v28, vcc, v25, v23, v25
	v_mul_f32_e32 v29, v28, v27
	v_fma_f32 v34, -v26, v29, v28
	v_fmac_f32_e32 v29, v34, v27
	v_fma_f32 v26, -v26, v29, v28
	v_div_fmas_f32 v26, v26, v27, v29
	v_div_fixup_f32 v23, v26, v23, v25
	v_div_scale_f32 v25, s[0:1], v22, v22, v24
	v_rcp_f32_e32 v26, v25
	v_pk_mul_f32 v[20:21], v[0:1], v[20:21] op_sel_hi:[0,1]
	v_fma_f32 v27, -v25, v26, 1.0
	v_fmac_f32_e32 v26, v27, v26
	v_div_scale_f32 v27, vcc, v24, v22, v24
	v_mul_f32_e32 v28, v27, v26
	v_fma_f32 v29, -v25, v28, v27
	v_fmac_f32_e32 v28, v29, v26
	v_fma_f32 v25, -v25, v28, v27
	v_div_fmas_f32 v25, v25, v26, v28
	v_div_fixup_f32 v22, v25, v22, v24
	v_pk_mul_f32 v[20:21], v[22:23], v[20:21]
	s_waitcnt vmcnt(9)
	v_lshlrev_b32_e32 v22, 16, v80
	v_and_b32_e32 v23, 0xffff0000, v80
	v_cvt_pk_bf16_f32 v137, v20, v21
	v_mul_f32_e32 v20, 0xbfb8aa3b, v22
	v_mul_f32_e32 v21, 0xbfb8aa3b, v23
	v_exp_f32_e32 v20, v20
	v_exp_f32_e32 v21, v21
	ds_read2st64_b32 v[18:19], v104 offset0:44 offset1:45
	v_pk_add_f32 v[20:21], v[20:21], 1.0 op_sel_hi:[1,0]
	s_nop 0
	v_div_scale_f32 v24, s[0:1], v21, v21, v23
	v_rcp_f32_e32 v25, v24
	s_waitcnt lgkmcnt(0)
	v_pk_mul_f32 v[18:19], v[72:73], v[18:19] op_sel_hi:[0,1]
	v_pk_fma_f32 v[18:19], v[30:31], v[66:67], v[18:19] op_sel_hi:[1,0,1]
	v_fma_f32 v26, -v24, v25, 1.0
	v_fmac_f32_e32 v25, v26, v25
	v_div_scale_f32 v26, vcc, v23, v21, v23
	v_mul_f32_e32 v27, v26, v25
	v_fma_f32 v28, -v24, v27, v26
	v_fmac_f32_e32 v27, v28, v25
	v_fma_f32 v24, -v24, v27, v26
	v_div_fmas_f32 v24, v24, v25, v27
	v_div_fixup_f32 v21, v24, v21, v23
	v_div_scale_f32 v23, s[0:1], v20, v20, v22
	v_rcp_f32_e32 v24, v23
	v_pk_mul_f32 v[18:19], v[0:1], v[18:19] op_sel_hi:[0,1]
	v_fma_f32 v25, -v23, v24, 1.0
	v_fmac_f32_e32 v24, v25, v24
	v_div_scale_f32 v25, vcc, v22, v20, v22
	v_mul_f32_e32 v26, v25, v24
	v_fma_f32 v27, -v23, v26, v25
	v_fmac_f32_e32 v26, v27, v24
	v_fma_f32 v23, -v23, v26, v25
	v_div_fmas_f32 v23, v23, v24, v26
	v_lshlrev_b32_e32 v24, 16, v81
	v_and_b32_e32 v25, 0xffff0000, v81
	v_div_fixup_f32 v20, v23, v20, v22
	v_mul_f32_e32 v22, 0xbfb8aa3b, v24
	v_mul_f32_e32 v23, 0xbfb8aa3b, v25
	v_exp_f32_e32 v22, v22
	v_exp_f32_e32 v23, v23
	v_pk_mul_f32 v[18:19], v[20:21], v[18:19]
	ds_read2st64_b32 v[20:21], v104 offset0:46 offset1:47
	v_cvt_pk_bf16_f32 v138, v18, v19
	v_pk_add_f32 v[22:23], v[22:23], 1.0 op_sel_hi:[1,0]
	s_waitcnt lgkmcnt(0)
; DI unsigned pk2(float lo, float hi) { f32x2 v = {lo, hi}; return __builtin_bit_cast(unsigned, __builtin_convertvector(v, bf2_t)); }
; DI float bflo(unsigned w) { return __uint_as_float(w << 16); }
; DI float bfhi(unsigned w) { return __uint_as_float(w & 0xffff0000u); }
; DI void attn_unit(const Params& p, int b, int h, int qb, LAS unsigned char* lds, int tid, int lane, int wave) {
;     ...
; #pragma unroll
;         for (int i = 0; i < 4; ++i)
; #pragma unroll
;             for (int q = 0; q < 4; ++q) {
;                 float gv[4] = {bflo(gw[i][q].x), bfhi(gw[i][q].x), bflo(gw[i][q].y), bfhi(gw[i][q].y)}; float ov[4];
; #pragma unroll
;                 for (int e = 0; e < 4; ++e) { const float val = (o[i][q * 4 + e] * a0 + MB[(i * 16 + q * 4 + e) * 64] * a1) * inv; ov[e] = val * (gv[e] / (1.f + __expf(-gv[e]))); }
;                 *(u32x2*)(op + i * 32 + q * 8) = (u32x2){pk2(ov[0], ov[1]), pk2(ov[2], ov[3])};
;             }
	v_pk_mul_f32 v[20:21], v[72:73], v[20:21] op_sel_hi:[0,1]
	v_div_scale_f32 v26, s[0:1], v23, v23, v25
	v_rcp_f32_e32 v27, v26
	v_pk_fma_f32 v[20:21], v[32:33], v[66:67], v[20:21] op_sel_hi:[1,0,1]
	v_fma_f32 v28, -v26, v27, 1.0
	v_fmac_f32_e32 v27, v28, v27
	v_div_scale_f32 v28, vcc, v25, v23, v25
	v_mul_f32_e32 v29, v28, v27
	v_fma_f32 v30, -v26, v29, v28
	v_fmac_f32_e32 v29, v30, v27
	v_fma_f32 v26, -v26, v29, v28
	v_div_fmas_f32 v26, v26, v27, v29
	v_div_fixup_f32 v23, v26, v23, v25
	v_div_scale_f32 v25, s[0:1], v22, v22, v24
	v_rcp_f32_e32 v26, v25
	v_pk_mul_f32 v[20:21], v[0:1], v[20:21] op_sel_hi:[0,1]
	v_fma_f32 v27, -v25, v26, 1.0
	v_fmac_f32_e32 v26, v27, v26
	v_div_scale_f32 v27, vcc, v24, v22, v24
	v_mul_f32_e32 v28, v27, v26
	v_fma_f32 v29, -v25, v28, v27
	v_fmac_f32_e32 v28, v29, v26
	v_fma_f32 v25, -v25, v28, v27
	v_div_fmas_f32 v25, v25, v26, v28
	v_div_fixup_f32 v22, v25, v22, v24
	v_pk_mul_f32 v[20:21], v[22:23], v[20:21]
	s_waitcnt vmcnt(8)
	v_lshlrev_b32_e32 v22, 16, v78
	v_cvt_pk_bf16_f32 v139, v20, v21
	s_nop 1
	v_permlane32_swap_b32_e32 v136, v138
	v_permlane32_swap_b32_e32 v137, v139
	global_store_dwordx4 v[148:149], v[136:139], off offset:160
	ds_read2st64_b32 v[18:19], v104 offset0:48 offset1:49
	v_and_b32_e32 v23, 0xffff0000, v78
	v_mul_f32_e32 v20, 0xbfb8aa3b, v22
	v_exp_f32_e32 v20, v20
	s_waitcnt lgkmcnt(0)
	v_pk_mul_f32 v[18:19], v[72:73], v[18:19] op_sel_hi:[0,1]
	v_pk_fma_f32 v[2:3], v[2:3], v[66:67], v[18:19] op_sel_hi:[1,0,1]
	v_mul_f32_e32 v18, 0xbfb8aa3b, v23
	v_exp_f32_e32 v21, v18
	v_pk_mul_f32 v[2:3], v[0:1], v[2:3] op_sel_hi:[0,1]
	v_pk_add_f32 v[18:19], v[20:21], 1.0 op_sel_hi:[1,0]
	s_nop 0
	v_rcp_f32_e32 v21, v19
	s_nop 0
	v_mul_f32_e32 v19, v23, v21
	v_rcp_f32_e32 v21, v18
	s_nop 0
	v_mul_f32_e32 v18, v22, v21
	v_pk_mul_f32 v[2:3], v[18:19], v[2:3]
	ds_read2st64_b32 v[18:19], v104 offset0:50 offset1:51
	v_lshlrev_b32_e32 v22, 16, v79
	v_and_b32_e32 v23, 0xffff0000, v79
	v_mul_f32_e32 v20, 0xbfb8aa3b, v22
	v_exp_f32_e32 v20, v20
	s_waitcnt lgkmcnt(0)
	v_pk_mul_f32 v[18:19], v[72:73], v[18:19] op_sel_hi:[0,1]
	v_pk_fma_f32 v[4:5], v[4:5], v[66:67], v[18:19] op_sel_hi:[1,0,1]
	v_mul_f32_e32 v18, 0xbfb8aa3b, v23
	v_exp_f32_e32 v21, v18
	v_pk_mul_f32 v[4:5], v[0:1], v[4:5] op_sel_hi:[0,1]
	v_cvt_pk_bf16_f32 v140, v2, v3
	v_pk_add_f32 v[18:19], v[20:21], 1.0 op_sel_hi:[1,0]
	s_nop 0
	v_rcp_f32_e32 v21, v19
	s_nop 0
	v_mul_f32_e32 v19, v23, v21
	v_rcp_f32_e32 v21, v18
	s_nop 0
	v_mul_f32_e32 v18, v22, v21
	v_pk_mul_f32 v[4:5], v[18:19], v[4:5]
	s_waitcnt vmcnt(8)
	v_lshlrev_b32_e32 v18, 16, v76
	v_cvt_pk_bf16_f32 v141, v4, v5
	v_and_b32_e32 v19, 0xffff0000, v76
	ds_read2st64_b32 v[2:3], v104 offset0:52 offset1:53
	v_mul_f32_e32 v4, 0xbfb8aa3b, v18
	v_mul_f32_e32 v5, 0xbfb8aa3b, v19
	v_exp_f32_e32 v4, v4
	v_exp_f32_e32 v5, v5
	s_waitcnt lgkmcnt(0)
	v_pk_mul_f32 v[2:3], v[72:73], v[2:3] op_sel_hi:[0,1]
	v_pk_fma_f32 v[2:3], v[6:7], v[66:67], v[2:3] op_sel_hi:[1,0,1]
	v_pk_add_f32 v[4:5], v[4:5], 1.0 op_sel_hi:[1,0]
	s_nop 0
	v_div_scale_f32 v6, s[0:1], v5, v5, v19
	v_rcp_f32_e32 v7, v6
	v_pk_mul_f32 v[2:3], v[0:1], v[2:3] op_sel_hi:[0,1]
	v_fma_f32 v20, -v6, v7, 1.0
	v_fmac_f32_e32 v7, v20, v7
	v_div_scale_f32 v20, vcc, v19, v5, v19
	v_mul_f32_e32 v21, v20, v7
	v_fma_f32 v22, -v6, v21, v20
	v_fmac_f32_e32 v21, v22, v7
	v_fma_f32 v6, -v6, v21, v20
	v_div_fmas_f32 v6, v6, v7, v21
	v_div_fixup_f32 v5, v6, v5, v19
	v_rcp_f32_e32 v7, v4
	s_nop 0
	v_mul_f32_e32 v4, v18, v7
	v_lshlrev_b32_e32 v18, 16, v77
	v_and_b32_e32 v19, 0xffff0000, v77
	v_pk_mul_f32 v[2:3], v[4:5], v[2:3]
	ds_read2st64_b32 v[4:5], v104 offset0:54 offset1:55
	v_mul_f32_e32 v6, 0xbfb8aa3b, v18
	v_mul_f32_e32 v7, 0xbfb8aa3b, v19
	v_exp_f32_e32 v6, v6
	v_exp_f32_e32 v7, v7
	s_waitcnt lgkmcnt(0)
	v_pk_mul_f32 v[4:5], v[72:73], v[4:5] op_sel_hi:[0,1]
	v_pk_fma_f32 v[4:5], v[8:9], v[66:67], v[4:5] op_sel_hi:[1,0,1]
	v_cvt_pk_bf16_f32 v142, v2, v3
	v_pk_add_f32 v[6:7], v[6:7], 1.0 op_sel_hi:[1,0]
	v_pk_mul_f32 v[4:5], v[0:1], v[4:5] op_sel_hi:[0,1]
	v_rcp_f32_e32 v9, v7
	s_nop 0
	v_mul_f32_e32 v7, v19, v9
	v_rcp_f32_e32 v9, v6
	s_nop 0
	v_mul_f32_e32 v6, v18, v9
	v_pk_mul_f32 v[4:5], v[6:7], v[4:5]
	s_waitcnt vmcnt(7)
	v_lshlrev_b32_e32 v6, 16, v74
	v_and_b32_e32 v7, 0xffff0000, v74
	v_cvt_pk_bf16_f32 v143, v4, v5
	v_mul_f32_e32 v4, 0xbfb8aa3b, v6
	v_mul_f32_e32 v5, 0xbfb8aa3b, v7
	v_exp_f32_e32 v4, v4
	v_exp_f32_e32 v5, v5
	s_nop 1
	v_permlane32_swap_b32_e32 v140, v142
	v_permlane32_swap_b32_e32 v141, v143
	global_store_dwordx4 v[148:149], v[140:143], off offset:192
	ds_read2st64_b32 v[2:3], v104 offset0:56 offset1:57
	v_pk_add_f32 v[4:5], v[4:5], 1.0 op_sel_hi:[1,0]
	s_nop 0
	v_div_scale_f32 v8, s[0:1], v5, v5, v7
	v_rcp_f32_e32 v9, v8
	s_waitcnt lgkmcnt(0)
	v_pk_mul_f32 v[2:3], v[72:73], v[2:3] op_sel_hi:[0,1]
	v_pk_fma_f32 v[2:3], v[10:11], v[66:67], v[2:3] op_sel_hi:[1,0,1]
	v_fma_f32 v10, -v8, v9, 1.0
	v_fmac_f32_e32 v9, v10, v9
	v_div_scale_f32 v10, vcc, v7, v5, v7
	v_mul_f32_e32 v11, v10, v9
	v_fma_f32 v18, -v8, v11, v10
	v_fmac_f32_e32 v11, v18, v9
	v_fma_f32 v8, -v8, v11, v10
	v_div_fmas_f32 v8, v8, v9, v11
	v_div_fixup_f32 v5, v8, v5, v7
	v_div_scale_f32 v7, s[0:1], v4, v4, v6
	v_rcp_f32_e32 v8, v7
	v_pk_mul_f32 v[2:3], v[0:1], v[2:3] op_sel_hi:[0,1]
	v_fma_f32 v9, -v7, v8, 1.0
	v_fmac_f32_e32 v8, v9, v8
	v_div_scale_f32 v9, vcc, v6, v4, v6
	v_mul_f32_e32 v10, v9, v8
	v_fma_f32 v11, -v7, v10, v9
	v_fmac_f32_e32 v10, v11, v8
	v_fma_f32 v7, -v7, v10, v9
	v_div_fmas_f32 v7, v7, v8, v10
	v_lshlrev_b32_e32 v8, 16, v75
	v_and_b32_e32 v9, 0xffff0000, v75
	v_div_fixup_f32 v4, v7, v4, v6
	v_mul_f32_e32 v6, 0xbfb8aa3b, v8
	v_mul_f32_e32 v7, 0xbfb8aa3b, v9
	v_exp_f32_e32 v6, v6
	v_exp_f32_e32 v7, v7
	v_pk_mul_f32 v[2:3], v[4:5], v[2:3]
	ds_read2st64_b32 v[4:5], v104 offset0:58 offset1:59
	v_cvt_pk_bf16_f32 v144, v2, v3
	v_pk_add_f32 v[6:7], v[6:7], 1.0 op_sel_hi:[1,0]
	s_waitcnt lgkmcnt(0)
; DI unsigned pk2(float lo, float hi) { f32x2 v = {lo, hi}; return __builtin_bit_cast(unsigned, __builtin_convertvector(v, bf2_t)); }
; DI float bflo(unsigned w) { return __uint_as_float(w << 16); }
; DI float bfhi(unsigned w) { return __uint_as_float(w & 0xffff0000u); }
; DI void attn_unit(const Params& p, int b, int h, int qb, LAS unsigned char* lds, int tid, int lane, int wave) {
;     ...
; #pragma unroll
;         for (int i = 0; i < 4; ++i)
; #pragma unroll
;             for (int q = 0; q < 4; ++q) {
;                 float gv[4] = {bflo(gw[i][q].x), bfhi(gw[i][q].x), bflo(gw[i][q].y), bfhi(gw[i][q].y)}; float ov[4];
; #pragma unroll
;                 for (int e = 0; e < 4; ++e) { const float val = (o[i][q * 4 + e] * a0 + MB[(i * 16 + q * 4 + e) * 64] * a1) * inv; ov[e] = val * (gv[e] / (1.f + __expf(-gv[e]))); }
;                 *(u32x2*)(op + i * 32 + q * 8) = (u32x2){pk2(ov[0], ov[1]), pk2(ov[2], ov[3])};
;             }
	v_pk_mul_f32 v[4:5], v[72:73], v[4:5] op_sel_hi:[0,1]
	v_div_scale_f32 v10, s[0:1], v7, v7, v9
	v_rcp_f32_e32 v11, v10
	v_pk_fma_f32 v[4:5], v[12:13], v[66:67], v[4:5] op_sel_hi:[1,0,1]
	v_fma_f32 v12, -v10, v11, 1.0
	v_fmac_f32_e32 v11, v12, v11
	v_div_scale_f32 v12, vcc, v9, v7, v9
	v_mul_f32_e32 v13, v12, v11
	v_fma_f32 v18, -v10, v13, v12
	v_fmac_f32_e32 v13, v18, v11
	v_fma_f32 v10, -v10, v13, v12
	v_div_fmas_f32 v10, v10, v11, v13
	v_div_fixup_f32 v7, v10, v7, v9
	v_div_scale_f32 v9, s[0:1], v6, v6, v8
	v_rcp_f32_e32 v10, v9
	v_pk_mul_f32 v[4:5], v[0:1], v[4:5] op_sel_hi:[0,1]
	v_fma_f32 v11, -v9, v10, 1.0
	v_fmac_f32_e32 v10, v11, v10
	v_div_scale_f32 v11, vcc, v8, v6, v8
	v_mul_f32_e32 v12, v11, v10
	v_fma_f32 v13, -v9, v12, v11
	v_fmac_f32_e32 v12, v13, v10
	v_fma_f32 v9, -v9, v12, v11
	v_div_fmas_f32 v9, v9, v10, v12
	v_div_fixup_f32 v6, v9, v6, v8
	v_pk_mul_f32 v[4:5], v[6:7], v[4:5]
	s_waitcnt vmcnt(7)
	v_lshlrev_b32_e32 v6, 16, v70
	v_and_b32_e32 v7, 0xffff0000, v70
	v_cvt_pk_bf16_f32 v145, v4, v5
	v_mul_f32_e32 v4, 0xbfb8aa3b, v6
	v_mul_f32_e32 v5, 0xbfb8aa3b, v7
	v_exp_f32_e32 v4, v4
	v_exp_f32_e32 v5, v5
	ds_read2st64_b32 v[2:3], v104 offset0:60 offset1:61
	v_pk_add_f32 v[4:5], v[4:5], 1.0 op_sel_hi:[1,0]
	s_nop 0
	v_div_scale_f32 v8, s[0:1], v5, v5, v7
	v_rcp_f32_e32 v9, v8
	s_waitcnt lgkmcnt(0)
	v_pk_mul_f32 v[2:3], v[72:73], v[2:3] op_sel_hi:[0,1]
	v_pk_fma_f32 v[2:3], v[14:15], v[66:67], v[2:3] op_sel_hi:[1,0,1]
	v_fma_f32 v10, -v8, v9, 1.0
	v_fmac_f32_e32 v9, v10, v9
	v_div_scale_f32 v10, vcc, v7, v5, v7
	v_mul_f32_e32 v11, v10, v9
	v_fma_f32 v12, -v8, v11, v10
	v_fmac_f32_e32 v11, v12, v9
	v_fma_f32 v8, -v8, v11, v10
	v_div_fmas_f32 v8, v8, v9, v11
	v_div_fixup_f32 v5, v8, v5, v7
	v_div_scale_f32 v7, s[0:1], v4, v4, v6
	v_rcp_f32_e32 v8, v7
	v_pk_mul_f32 v[2:3], v[0:1], v[2:3] op_sel_hi:[0,1]
	v_fma_f32 v9, -v7, v8, 1.0
	v_fmac_f32_e32 v8, v9, v8
	v_div_scale_f32 v9, vcc, v6, v4, v6
	v_mul_f32_e32 v10, v9, v8
	v_fma_f32 v11, -v7, v10, v9
	v_fmac_f32_e32 v10, v11, v8
	v_fma_f32 v7, -v7, v10, v9
	v_div_fmas_f32 v7, v7, v8, v10
	v_div_fixup_f32 v4, v7, v4, v6
	v_pk_mul_f32 v[2:3], v[4:5], v[2:3]
	ds_read2st64_b32 v[4:5], v104 offset0:62 offset1:63
	v_lshlrev_b32_e32 v8, 16, v71
	v_and_b32_e32 v9, 0xffff0000, v71
	v_mul_f32_e32 v6, 0xbfb8aa3b, v8
	v_exp_f32_e32 v6, v6
	s_waitcnt lgkmcnt(0)
	v_pk_mul_f32 v[4:5], v[72:73], v[4:5] op_sel_hi:[0,1]
	v_pk_fma_f32 v[4:5], v[16:17], v[66:67], v[4:5] op_sel_hi:[1,0,1]
	v_cvt_pk_bf16_f32 v146, v2, v3
	v_pk_mul_f32 v[4:5], v[0:1], v[4:5] op_sel_hi:[0,1]
	v_mul_f32_e32 v0, 0xbfb8aa3b, v9
	v_exp_f32_e32 v7, v0
	s_nop 0
	v_pk_add_f32 v[6:7], v[6:7], 1.0 op_sel_hi:[1,0]
	s_nop 0
	v_rcp_f32_e32 v10, v7
	s_nop 0
	v_mul_f32_e32 v7, v9, v10
	v_rcp_f32_e32 v9, v6
	s_nop 0
	v_mul_f32_e32 v6, v8, v9
	v_pk_mul_f32 v[4:5], v[6:7], v[4:5]
	s_nop 0
	v_cvt_pk_bf16_f32 v147, v4, v5
	s_nop 1
	v_permlane32_swap_b32_e32 v144, v146
	v_permlane32_swap_b32_e32 v145, v147
	global_store_dwordx4 v[148:149], v[144:147], off offset:224
	s_branch .LBB0_425
.LBB0_462:
	s_or_b64 exec, exec, s[22:23]
	s_waitcnt vmcnt(24)
	v_lshlrev_b32_e32 v54, 16, v150
	v_or_b32_sdwa v147, v54, v149 dst_sel:DWORD dst_unused:UNUSED_PAD src0_sel:DWORD src1_sel:WORD_0
	s_waitcnt vmcnt(22)
	v_lshlrev_b32_e32 v54, 16, v152
	v_or_b32_sdwa v145, v54, v151 dst_sel:DWORD dst_unused:UNUSED_PAD src0_sel:DWORD src1_sel:WORD_0
	s_waitcnt vmcnt(20)
	v_lshlrev_b32_e32 v54, 16, v154
	v_or_b32_sdwa v144, v54, v153 dst_sel:DWORD dst_unused:UNUSED_PAD src0_sel:DWORD src1_sel:WORD_0
	s_waitcnt vmcnt(18)
	v_lshlrev_b32_e32 v54, 16, v156
	v_or_b32_sdwa v143, v54, v155 dst_sel:DWORD dst_unused:UNUSED_PAD src0_sel:DWORD src1_sel:WORD_0
	s_waitcnt vmcnt(16)
	v_lshlrev_b32_e32 v54, 16, v158
	v_or_b32_sdwa v137, v54, v157 dst_sel:DWORD dst_unused:UNUSED_PAD src0_sel:DWORD src1_sel:WORD_0
	s_waitcnt vmcnt(14)
	v_lshlrev_b32_e32 v54, 16, v160
	v_or_b32_sdwa v136, v54, v159 dst_sel:DWORD dst_unused:UNUSED_PAD src0_sel:DWORD src1_sel:WORD_0
	s_waitcnt vmcnt(12)
	v_lshlrev_b32_e32 v54, 16, v162
	v_or_b32_sdwa v135, v54, v161 dst_sel:DWORD dst_unused:UNUSED_PAD src0_sel:DWORD src1_sel:WORD_0
	s_waitcnt vmcnt(10)
	v_lshlrev_b32_e32 v54, 16, v164
	s_add_i32 s28, 0, 0x13000
	v_or_b32_sdwa v134, v54, v163 dst_sel:DWORD dst_unused:UNUSED_PAD src0_sel:DWORD src1_sel:WORD_0
	v_add_u32_e32 v54, s28, v88
	s_waitcnt lgkmcnt(0)
	s_barrier
; #define LAS __attribute__((address_space(3)))
; DI bf16_t f2bf(float f) { return (bf16_t)(pk2(f, 0.f) & 0xffffu); }
; DI float bf2f(bf16_t b) { return __uint_as_float((unsigned)b << 16); }
; DI void gla_compute3(const Params& p, int item, const GlaIn<true>& g, LAS unsigned char* lds, int tid, int lane, int wave) {
;     ...
;     {
;         const LAS bf16_t* GTt = (const LAS bf16_t*)(lds + GL_GT); LAS bf16_t* OTt = (LAS bf16_t*)(lds + GL_OT);
; #pragma unroll
;         for (int r = 0; r < 4; ++r) { const int i = mt * 16 + fq * 4 + r; const float rstd = rsqrtf((RS[i * 2] + RS[i * 2 + 1]) * (1.0f / 128.0f) + EPS);
; #pragma unroll
;             for (int n = 0; n < 4; ++n) { const int dv = hf * 64 + n * 16 + fr;
;                 const float gg = bf2f(GTt[i * 136 + dv]);
;                 OTt[i * 136 + dv] = f2bf(acc[n][r] * rstd * g.gn[n] * (gg / (1.f + __expf(-gg)))); } }
;     }
	ds_read_b128 v[54:57], v54
	ds_read_u16 v58, v90
	s_brev_b32 s30, 60
	s_lshl_b32 s3, s21, 4
	s_and_b32 s3, s3, 0x3fc0
	s_lshl_b32 s21, s21, 8
	s_waitcnt lgkmcnt(0)
	v_lshlrev_b32_e32 v58, 16, v58
	v_mul_f32_e32 v59, 0xbfb8aa3b, v58
	v_exp_f32_e32 v59, v59
	s_and_b32 s92, s21, 0x300
	s_mov_b32 s21, s20
	v_add_f32_e32 v59, 1.0, v59
	v_rcp_f32_e32 v61, v59
	s_nop 0
	v_mul_f32_e32 v60, v58, v61
	ds_read_u16 v58, v92
	s_waitcnt lgkmcnt(0)
	v_lshlrev_b32_e32 v58, 16, v58
	v_mul_f32_e32 v59, 0xbfb8aa3b, v58
	v_exp_f32_e32 v59, v59
	s_nop 0
	v_add_f32_e32 v59, 1.0, v59
	v_rcp_f32_e32 v62, v59
	s_nop 0
	v_mul_f32_e32 v61, v58, v62
	ds_read_u16 v58, v94
	s_waitcnt lgkmcnt(0)
	v_lshlrev_b32_e32 v58, 16, v58
	v_mul_f32_e32 v59, 0xbfb8aa3b, v58
	v_exp_f32_e32 v59, v59
	s_nop 0
	v_add_f32_e32 v59, 1.0, v59
	v_rcp_f32_e32 v63, v59
	s_nop 0
	v_mul_f32_e32 v62, v58, v63
	ds_read_u16 v58, v96
	s_waitcnt lgkmcnt(0)
	v_lshlrev_b32_e32 v58, 16, v58
	v_mul_f32_e32 v59, 0xbfb8aa3b, v58
	v_exp_f32_e32 v59, v59
	s_nop 0
	v_add_f32_e32 v59, 1.0, v59
	v_rcp_f32_e32 v64, v59
	s_nop 0
	v_mul_f32_e32 v63, v58, v64
	v_mov_b32_e32 v58, v56
	v_mov_b32_e32 v59, v54
	v_mov_b32_e32 v54, v57
	v_pk_add_f32 v[54:55], v[58:59], v[54:55]
	v_mov_b64_e32 v[58:59], s[90:91]
	v_pk_fma_f32 v[54:55], v[54:55], s[30:31], v[58:59] op_sel_hi:[1,0,0]
	s_nop 0
	v_mul_f32_e32 v56, 0x4b800000, v55
	v_cmp_gt_f32_e64 s[22:23], s95, v55
	v_cmp_gt_f32_e32 vcc, s95, v54
	s_nop 0
	v_cndmask_b32_e64 v55, v55, v56, s[22:23]
	v_rsq_f32_e32 v55, v55
	s_nop 0
	v_mul_f32_e32 v56, 0x45800000, v55
	v_cndmask_b32_e64 v55, v55, v56, s[22:23]
	v_mul_f32_e32 v38, v38, v55
	v_mul_f32_e32 v38, v119, v38
	v_mul_f32_e32 v38, v38, v63
	v_cvt_pk_bf16_f32 v38, v38, s0
	ds_write_b16 v97, v38
	v_mul_f32_e32 v38, 0x4b800000, v54
	v_cndmask_b32_e32 v38, v54, v38, vcc
	v_mul_f32_e32 v50, v50, v55
	v_mul_f32_e32 v46, v46, v55
	v_mul_f32_e32 v42, v42, v55
	v_rsq_f32_e32 v38, v38
	v_mul_f32_e32 v50, v148, v50
	v_mul_f32_e32 v46, v146, v46
	v_mul_f32_e32 v42, v138, v42
	v_mul_f32_e32 v50, v60, v50
	v_mul_f32_e32 v46, v46, v61
	v_mul_f32_e32 v42, v42, v62
	v_cvt_pk_bf16_f32 v50, v50, s0
	v_cvt_pk_bf16_f32 v46, v46, s0
	v_cvt_pk_bf16_f32 v42, v42, s0
	ds_write_b16 v91, v50
	ds_write_b16 v93, v46
	ds_write_b16 v95, v42
	v_mul_f32_e32 v42, 0x45800000, v38
	v_cndmask_b32_e32 v38, v38, v42, vcc
	ds_read_u16 v42, v98
	v_mul_f32_e32 v46, v51, v38
	v_mul_f32_e32 v46, v148, v46
	v_mul_f32_e32 v43, v43, v38
	v_mul_f32_e32 v43, v138, v43
	s_waitcnt lgkmcnt(0)
	v_lshlrev_b32_e32 v42, 16, v42
	v_mul_f32_e32 v50, 0xbfb8aa3b, v42
	v_exp_f32_e32 v50, v50
	s_nop 0
	v_add_f32_e32 v50, 1.0, v50
	v_rcp_f32_e32 v54, v50
	s_nop 0
	v_mul_f32_e32 v42, v42, v54
	v_mul_f32_e32 v42, v42, v46
	v_cvt_pk_bf16_f32 v42, v42, s0
	ds_write_b16 v99, v42
	ds_read_u16 v42, v100
	v_mul_f32_e32 v46, v47, v38
	v_mul_f32_e32 v46, v146, v46
	v_mul_f32_e32 v38, v39, v38
	v_mul_f32_e32 v38, v119, v38
	s_waitcnt lgkmcnt(0)
	v_lshlrev_b32_e32 v42, 16, v42
	v_mul_f32_e32 v47, 0xbfb8aa3b, v42
	v_exp_f32_e32 v47, v47
	s_nop 0
	v_add_f32_e32 v47, 1.0, v47
	v_rcp_f32_e32 v51, v47
	s_nop 0
	v_mul_f32_e32 v42, v42, v51
	v_mul_f32_e32 v42, v46, v42
	v_cvt_pk_bf16_f32 v42, v42, s0
	ds_write_b16 v101, v42
	ds_read_u16 v42, v102
	s_waitcnt lgkmcnt(0)
	v_lshlrev_b32_e32 v42, 16, v42
	v_mul_f32_e32 v46, 0xbfb8aa3b, v42
	v_exp_f32_e32 v46, v46
	s_nop 0
	v_add_f32_e32 v46, 1.0, v46
	v_rcp_f32_e32 v50, v46
	s_nop 0
	v_mul_f32_e32 v42, v42, v50
	v_mul_f32_e32 v42, v43, v42
	v_cvt_pk_bf16_f32 v42, v42, s0
	ds_write_b16 v103, v42
	ds_read_u16 v42, v104
	s_waitcnt lgkmcnt(0)
	v_lshlrev_b32_e32 v42, 16, v42
	v_mul_f32_e32 v39, 0xbfb8aa3b, v42
	v_exp_f32_e32 v39, v39
	s_nop 0
	v_add_f32_e32 v39, 1.0, v39
	v_rcp_f32_e32 v46, v39
	s_nop 0
	v_mul_f32_e32 v39, v42, v46
	v_mul_f32_e32 v38, v38, v39
	v_cvt_pk_bf16_f32 v38, v38, s0
	ds_write_b16 v105, v38
	v_add_u32_e32 v38, s28, v89
	ds_read_b128 v[54:57], v38
	ds_read_u16 v38, v106
	s_waitcnt lgkmcnt(0)
	v_lshlrev_b32_e32 v38, 16, v38
	v_mul_f32_e32 v39, 0xbfb8aa3b, v38
	v_exp_f32_e32 v39, v39
	s_nop 0
	v_add_f32_e32 v39, 1.0, v39
	v_rcp_f32_e32 v43, v39
	s_nop 0
	v_mul_f32_e32 v42, v38, v43
	ds_read_u16 v38, v108
	s_waitcnt lgkmcnt(0)
; #define LAS __attribute__((address_space(3)))
; DI bf16_t f2bf(float f) { return (bf16_t)(pk2(f, 0.f) & 0xffffu); }
; DI float bf2f(bf16_t b) { return __uint_as_float((unsigned)b << 16); }
; DI void gla_compute3(const Params& p, int item, const GlaIn<true>& g, LAS unsigned char* lds, int tid, int lane, int wave) {
;     ...
;         for (int r = 0; r < 4; ++r) { const int i = mt * 16 + fq * 4 + r; const float rstd = rsqrtf((RS[i * 2] + RS[i * 2 + 1]) * (1.0f / 128.0f) + EPS);
; #pragma unroll
;             for (int n = 0; n < 4; ++n) { const int dv = hf * 64 + n * 16 + fr;
;                 const float gg = bf2f(GTt[i * 136 + dv]);
;                 OTt[i * 136 + dv] = f2bf(acc[n][r] * rstd * g.gn[n] * (gg / (1.f + __expf(-gg)))); } }
;     }
;     __syncthreads();
; #pragma unroll
;     for (int e = 0; e < 2; ++e) { const int cc = tid + e * 512;
;         *(u32x4*)(OB + (size_t)(t0 + (cc >> 4)) * DM + h * 128 + (cc & 15) * 8) = *(const LAS u32x4*)(lds + GL_OT + (cc >> 4) * 272 + (cc & 15) * 16); }
	v_lshlrev_b32_e32 v38, 16, v38
	v_mul_f32_e32 v39, 0xbfb8aa3b, v38
	v_exp_f32_e32 v39, v39
	s_nop 0
	v_add_f32_e32 v39, 1.0, v39
	v_rcp_f32_e32 v46, v39
	s_nop 0
	v_mul_f32_e32 v43, v38, v46
	ds_read_u16 v38, v110
	s_waitcnt lgkmcnt(0)
	v_lshlrev_b32_e32 v38, 16, v38
	v_mul_f32_e32 v39, 0xbfb8aa3b, v38
	v_exp_f32_e32 v39, v39
	s_nop 0
	v_add_f32_e32 v39, 1.0, v39
	v_rcp_f32_e32 v47, v39
	s_nop 0
	v_mul_f32_e32 v46, v38, v47
	ds_read_u16 v38, v112
	s_waitcnt lgkmcnt(0)
	v_lshlrev_b32_e32 v38, 16, v38
	v_mul_f32_e32 v39, 0xbfb8aa3b, v38
	v_exp_f32_e32 v39, v39
	s_nop 0
	v_add_f32_e32 v39, 1.0, v39
	v_rcp_f32_e32 v50, v39
	s_nop 0
	v_mul_f32_e32 v47, v38, v50
	v_mov_b32_e32 v38, v56
	v_mov_b32_e32 v39, v54
	v_mov_b32_e32 v54, v57
	v_pk_add_f32 v[38:39], v[38:39], v[54:55]
	s_nop 0
	v_pk_fma_f32 v[38:39], v[38:39], s[30:31], v[58:59] op_sel_hi:[1,0,0]
	s_nop 0
	v_mul_f32_e32 v50, 0x4b800000, v39
	v_cmp_gt_f32_e64 s[22:23], s95, v39
	v_cmp_gt_f32_e32 vcc, s95, v38
	s_nop 0
	v_cndmask_b32_e64 v39, v39, v50, s[22:23]
	v_rsq_f32_e32 v39, v39
	s_nop 0
	v_mul_f32_e32 v50, 0x45800000, v39
	v_cndmask_b32_e64 v39, v39, v50, s[22:23]
	v_mul_f32_e32 v50, v52, v39
	v_mul_f32_e32 v50, v148, v50
	v_mul_f32_e32 v42, v42, v50
	v_cvt_pk_bf16_f32 v42, v42, s0
	ds_write_b16 v107, v42
	v_mul_f32_e32 v42, v48, v39
	v_mul_f32_e32 v42, v146, v42
	v_mul_f32_e32 v42, v42, v43
	v_cvt_pk_bf16_f32 v42, v42, s0
	ds_write_b16 v109, v42
	v_mul_f32_e32 v42, v44, v39
	v_mul_f32_e32 v39, v40, v39
	v_mul_f32_e32 v39, v119, v39
	v_mul_f32_e32 v39, v39, v47
	v_cvt_pk_bf16_f32 v39, v39, s0
	ds_write_b16 v113, v39
	v_mul_f32_e32 v39, 0x4b800000, v38
	v_cndmask_b32_e32 v38, v38, v39, vcc
	v_rsq_f32_e32 v38, v38
	v_mul_f32_e32 v42, v138, v42
	v_mul_f32_e32 v42, v42, v46
	v_cvt_pk_bf16_f32 v42, v42, s0
	ds_write_b16 v111, v42
	v_mul_f32_e32 v39, 0x45800000, v38
	v_cndmask_b32_e32 v38, v38, v39, vcc
	ds_read_u16 v39, v114
	v_mul_f32_e32 v40, v53, v38
	v_mul_f32_e32 v40, v148, v40
	s_waitcnt vmcnt(3)
	v_mov_b32_e32 v148, v139
	s_waitcnt lgkmcnt(0)
	v_lshlrev_b32_e32 v39, 16, v39
	v_mul_f32_e32 v42, 0xbfb8aa3b, v39
	v_exp_f32_e32 v42, v42
	s_nop 0
	v_add_f32_e32 v42, 1.0, v42
	v_rcp_f32_e32 v44, v42
	s_nop 0
	v_mul_f32_e32 v39, v39, v44
	v_mul_f32_e32 v39, v39, v40
	v_cvt_pk_bf16_f32 v39, v39, s0
	ds_write_b16 v115, v39
	ds_read_u16 v39, v116
	v_mul_f32_e32 v40, v49, v38
	v_mul_f32_e32 v40, v146, v40
	s_waitcnt vmcnt(2)
	v_mov_b32_e32 v146, v140
	s_waitcnt lgkmcnt(0)
	v_lshlrev_b32_e32 v39, 16, v39
	v_mul_f32_e32 v42, 0xbfb8aa3b, v39
	v_exp_f32_e32 v42, v42
	s_nop 0
	v_add_f32_e32 v42, 1.0, v42
	v_rcp_f32_e32 v44, v42
	s_nop 0
	v_mul_f32_e32 v39, v39, v44
	v_mul_f32_e32 v39, v40, v39
	v_cvt_pk_bf16_f32 v39, v39, s0
	ds_write_b16 v117, v39
	ds_read_u16 v39, v118
	v_mul_f32_e32 v40, v45, v38
	v_mul_f32_e32 v40, v138, v40
	v_mul_f32_e32 v38, v41, v38
	v_mul_f32_e32 v38, v119, v38
	s_waitcnt lgkmcnt(0)
	v_lshlrev_b32_e32 v39, 16, v39
	v_mul_f32_e32 v42, 0xbfb8aa3b, v39
	v_exp_f32_e32 v42, v42
	s_waitcnt vmcnt(1)
	v_mov_b32_e32 v138, v141
	s_waitcnt vmcnt(0)
	v_mov_b32_e32 v119, v142
	v_add_f32_e32 v42, 1.0, v42
	v_rcp_f32_e32 v44, v42
	s_nop 0
	v_mul_f32_e32 v39, v39, v44
	v_mul_f32_e32 v39, v40, v39
	v_cvt_pk_bf16_f32 v39, v39, s0
	ds_write_b16 v120, v39
	ds_read_u16 v39, v121
	s_waitcnt lgkmcnt(0)
	v_lshlrev_b32_e32 v39, 16, v39
	v_mul_f32_e32 v40, 0xbfb8aa3b, v39
	v_exp_f32_e32 v40, v40
	s_nop 0
	v_add_f32_e32 v40, 1.0, v40
	v_rcp_f32_e32 v42, v40
	s_nop 0
	v_mul_f32_e32 v39, v39, v42
	v_mul_f32_e32 v38, v38, v39
	v_cvt_pk_bf16_f32 v38, v38, s0
	ds_write_b16 v122, v38
	v_add_u32_e32 v38, v87, v84
	s_waitcnt lgkmcnt(0)
	s_barrier
	ds_read_b128 v[38:41], v38
	v_add_u32_e32 v44, s3, v71
	v_ashrrev_i32_e32 v45, 31, v44
	v_lshl_add_u64 v[42:43], v[78:79], 0, s[92:93]
	v_lshlrev_b64 v[44:45], 11, v[44:45]
	v_lshl_add_u64 v[44:45], v[42:43], 0, v[44:45]
	s_waitcnt lgkmcnt(0)
	global_store_dwordx4 v[44:45], v[38:41], off
	v_add_u32_e32 v44, s3, v82
	v_ashrrev_i32_e32 v45, 31, v44
	v_add_u32_e32 v38, v87, v85
	ds_read_b128 v[38:41], v38
	v_lshlrev_b64 v[44:45], 11, v[44:45]
	v_lshl_add_u64 v[42:43], v[42:43], 0, v[44:45]
	s_andn2_b64 vcc, exec, s[26:27]
	s_waitcnt lgkmcnt(0)
	global_store_dwordx4 v[42:43], v[38:41], off
	s_barrier
	s_cbranch_vccz .LBB0_465
